# v34 + nt cache policy on the fp16 residual-base loads of the gated-residual epilogues, the phase-18 norm row loads and the LRU backward pass's forward-state / gate loads
# baseline (speedup 1.0000x reference)
; #define GAS __attribute__((address_space(1)))
;     __device__ __forceinline__ void operator()(const f32x4 (&acc)[2][2][4][2], const pg8::Unit& u, int wr, int wc, int fr, int fq) const {
;     ...
;         const int row0 = u.pm * 256 + wr * 64 + fr, col0 = u.pn * 256 + wc * 32 + 8 * fq;
;         const int r = u.pm < 64 ? (u.pm >> 3) : 8;
;         const float* gv = gate + (size_t)r * DMODW + col0;
;         f32x4 gvv[2][2];
; #pragma unroll
;         for (int bj = 0; bj < 2; ++bj)
; #pragma unroll
;             for (int n = 0; n < 2; ++n) gvv[bj][n] = *(const f32x4*)(gv + bj * 128 + 4 * n) * coef;
;         if (u.kind >= 2) {
;             GAS float* op = part + (size_t)(u.kind - 2) * (PART_STRIDE / 4) + (size_t)(row0 - M_LAT) * D + col0;
; #pragma unroll
;             for (int ai = 0; ai < 2; ++ai)
; #pragma unroll
;                 for (int m = 0; m < 4; ++m) { const size_t ro = (size_t)(ai * 128 + m * 16) * D;
; #pragma unroll
;                     for (int bj = 0; bj < 2; ++bj)
; #pragma unroll
;                         for (int n = 0; n < 2; ++n) *(GAS f32x4*)(op + ro + bj * 128 + 4 * n) = gvv[bj][n] * acc[ai][bj][m][n]; }
;             return;
;         }
;         const size_t eo = (u.pm < 64 ? (size_t)row0 : (size_t)(row0 - M_LAT)) * D + col0;
;         const void* bsel = u.pm < 64 ? base_lat : base_ctx;
;         const size_t oo = (size_t)row0 * D + col0;
;         if constexpr (!BASE_F32) {
;             u32x4 hb[2][4][2];
; #pragma unroll
;             for (int ai = 0; ai < 2; ++ai)
; #pragma unroll
;                 for (int m = 0; m < 4; ++m)
; #pragma unroll
;                     for (int bj = 0; bj < 2; ++bj) hb[ai][m][bj] = *(const u32x4*)((const _Float16*)bsel + eo + (size_t)(ai * 128 + m * 16) * D + bj * 128);
; #pragma unroll
;             for (int ai = 0; ai < 2; ++ai)
; #pragma unroll
;                 for (int m = 0; m < 4; ++m)
; #pragma unroll
;                     for (int bj = 0; bj < 2; ++bj) { const size_t ro = (size_t)(ai * 128 + m * 16) * D + bj * 128; const u32x4 hv = hb[ai][m][bj];
;                         const f32x4 v0 = h4_to_f32x4((u32x2){hv.x, hv.y}) + gvv[bj][0] * acc[ai][bj][m][0], v1 = h4_to_f32x4((u32x2){hv.z, hv.w}) + gvv[bj][1] * acc[ai][bj][m][1];
;                         if constexpr (OUT_F32) { *(f32x4*)((float*)out + oo + ro) = v0; *(f32x4*)((float*)out + oo + ro + 4) = v1; }
.LBB0_960:
	v_lshl_or_b32 v224, s20, 8, v231
	s_lshl_b64 s[20:21], s[24:25], 2
	s_add_u32 s20, s40, s20
	s_addc_u32 s21, s41, s21
	v_ashrrev_i32_e32 v225, 31, v224
	v_lshl_add_u64 v[134:135], v[224:225], 2, s[20:21]
	global_load_dwordx4 v[138:141], v[134:135], off offset:16
	global_load_dwordx4 v[142:145], v[134:135], off
	global_load_dwordx4 v[130:133], v[134:135], off offset:528
	s_nop 0
	global_load_dwordx4 v[134:137], v[134:135], off offset:512
	v_lshl_add_u32 v222, s22, 8, v229
	s_mov_b64 s[20:21], -1
	s_cmp_lt_i32 s71, 2
	v_ashrrev_i32_e32 v223, 31, v222
	s_cbranch_scc0 .LBB0_962
	v_add_u32_e32 v146, 0xffffc000, v222
	v_cndmask_b32_e32 v146, v146, v222, vcc
	v_readlane_b32 s24, v253, 52
	v_ashrrev_i32_e32 v147, 31, v146
	s_and_b64 s[20:21], vcc, exec
	v_readlane_b32 s25, v253, 53
	s_cselect_b32 s21, s25, s39
	s_cselect_b32 s20, s24, s38
	v_lshlrev_b64 v[146:147], 12, v[146:147]
	v_lshl_add_u64 v[146:147], s[20:21], 0, v[146:147]
	v_lshlrev_b64 v[226:227], 1, v[224:225]
	v_lshl_add_u64 v[146:147], v[146:147], 0, v[226:227]
	global_load_dwordx4 v[236:239], v[146:147], off nt
	global_load_dwordx4 v[202:205], v[146:147], off offset:256 nt
	v_add_co_u32_e32 v148, vcc, s37, v146
	v_lshlrev_b64 v[240:241], 12, v[222:223]
	s_nop 0
	v_addc_co_u32_e32 v149, vcc, 0, v147, vcc
	global_load_dwordx4 v[198:201], v[148:149], off nt
	global_load_dwordx4 v[194:197], v[148:149], off offset:256 nt
	v_add_co_u32_e32 v148, vcc, s49, v146
	v_lshl_add_u64 v[240:241], s[24:25], 0, v[240:241]
	s_nop 0
	v_addc_co_u32_e32 v149, vcc, 0, v147, vcc
	global_load_dwordx4 v[190:193], v[148:149], off nt
	global_load_dwordx4 v[186:189], v[148:149], off offset:256 nt
	v_add_co_u32_e32 v148, vcc, s46, v146
	v_lshl_add_u64 v[226:227], v[240:241], 0, v[226:227]
	s_nop 0
	v_addc_co_u32_e32 v149, vcc, 0, v147, vcc
	global_load_dwordx4 v[182:185], v[148:149], off nt
	global_load_dwordx4 v[178:181], v[148:149], off offset:256 nt
	v_add_co_u32_e32 v148, vcc, s50, v146
	s_mov_b64 s[20:21], 0
	s_nop 0
	v_addc_co_u32_e32 v149, vcc, 0, v147, vcc
	global_load_dwordx4 v[174:177], v[148:149], off nt
	global_load_dwordx4 v[170:173], v[148:149], off offset:256 nt
	v_add_co_u32_e32 v148, vcc, s51, v146
	s_waitcnt vmcnt(0)
	v_cvt_f32_f16_e32 v242, v237
	v_cvt_f32_f16_sdwa v243, v237 dst_sel:DWORD dst_unused:UNUSED_PAD src0_sel:WORD_1
	v_cvt_f32_f16_e32 v244, v236
	v_cvt_f32_f16_sdwa v245, v236 dst_sel:DWORD dst_unused:UNUSED_PAD src0_sel:WORD_1
	v_cvt_f32_f16_e32 v246, v238
	v_pk_fma_f32 v[236:237], v[128:129], v[144:145], v[242:243]
	v_cvt_f32_f16_e32 v242, v239
	v_cvt_f32_f16_sdwa v243, v239 dst_sel:DWORD dst_unused:UNUSED_PAD src0_sel:WORD_1
	v_cvt_f32_f16_sdwa v247, v238 dst_sel:DWORD dst_unused:UNUSED_PAD src0_sel:WORD_1
	v_addc_co_u32_e32 v149, vcc, 0, v147, vcc
	global_load_dwordx4 v[166:169], v[148:149], off nt
	global_load_dwordx4 v[162:165], v[148:149], off offset:256 nt
	v_add_co_u32_e32 v148, vcc, s68, v146
	v_pk_fma_f32 v[244:245], v[126:127], v[142:143], v[244:245]
	s_nop 0
	v_addc_co_u32_e32 v149, vcc, 0, v147, vcc
	v_add_co_u32_e32 v146, vcc, s69, v146
	v_pk_fma_f32 v[246:247], v[122:123], v[138:139], v[246:247]
	v_pk_fma_f32 v[238:239], v[124:125], v[140:141], v[242:243]
	v_addc_co_u32_e32 v147, vcc, 0, v147, vcc
	v_cvt_pk_f16_f32 v237, v236, v237
	v_cvt_pk_f16_f32 v236, v244, v245
	v_cvt_pk_f16_f32 v239, v238, v239
	v_cvt_pk_f16_f32 v238, v246, v247
	global_load_dwordx4 v[158:161], v[148:149], off nt
	global_load_dwordx4 v[154:157], v[148:149], off offset:256 nt
	global_load_dwordx4 v[150:153], v[146:147], off nt
	s_nop 0
	global_load_dwordx4 v[146:149], v[146:147], off offset:256 nt
	v_cvt_f32_f16_e32 v240, v204
	global_store_dwordx4 v[226:227], v[236:239], off
	v_cvt_f32_f16_sdwa v241, v204 dst_sel:DWORD dst_unused:UNUSED_PAD src0_sel:WORD_1
	v_pk_fma_f32 v[240:241], v[106:107], v[130:131], v[240:241]
	v_cvt_f32_f16_e32 v236, v203
	v_cvt_f32_f16_sdwa v237, v203 dst_sel:DWORD dst_unused:UNUSED_PAD src0_sel:WORD_1
	v_cvt_f32_f16_e32 v238, v202
	v_cvt_f32_f16_sdwa v239, v202 dst_sel:DWORD dst_unused:UNUSED_PAD src0_sel:WORD_1
	v_pk_fma_f32 v[202:203], v[116:117], v[136:137], v[236:237]
	v_cvt_f32_f16_e32 v236, v205
	v_cvt_f32_f16_sdwa v237, v205 dst_sel:DWORD dst_unused:UNUSED_PAD src0_sel:WORD_1
	v_pk_fma_f32 v[238:239], v[114:115], v[134:135], v[238:239]
	v_cvt_pk_f16_f32 v203, v202, v203
	v_cvt_pk_f16_f32 v202, v238, v239
	v_pk_fma_f32 v[204:205], v[108:109], v[132:133], v[236:237]
	v_cvt_f32_f16_e32 v236, v200
	v_cvt_pk_f16_f32 v205, v204, v205
	v_cvt_pk_f16_f32 v204, v240, v241
	global_store_dwordx4 v[226:227], v[202:205], off offset:256
	v_cvt_f32_f16_sdwa v237, v200 dst_sel:DWORD dst_unused:UNUSED_PAD src0_sel:WORD_1
	v_pk_fma_f32 v[236:237], v[110:111], v[138:139], v[236:237]
	v_cvt_f32_f16_e32 v202, v199
	v_cvt_f32_f16_sdwa v203, v199 dst_sel:DWORD dst_unused:UNUSED_PAD src0_sel:WORD_1
	v_cvt_f32_f16_e32 v204, v198
	v_cvt_f32_f16_sdwa v205, v198 dst_sel:DWORD dst_unused:UNUSED_PAD src0_sel:WORD_1
	v_pk_fma_f32 v[198:199], v[120:121], v[144:145], v[202:203]
	v_cvt_f32_f16_e32 v202, v201
	v_cvt_f32_f16_sdwa v203, v201 dst_sel:DWORD dst_unused:UNUSED_PAD src0_sel:WORD_1
	v_pk_fma_f32 v[204:205], v[118:119], v[142:143], v[204:205]
	v_cvt_pk_f16_f32 v199, v198, v199
	v_cvt_pk_f16_f32 v198, v204, v205
	v_pk_fma_f32 v[200:201], v[112:113], v[140:141], v[202:203]
	v_add_co_u32_e32 v202, vcc, s37, v226
	v_cvt_pk_f16_f32 v201, v200, v201
	v_cvt_pk_f16_f32 v200, v236, v237
	v_addc_co_u32_e32 v203, vcc, 0, v227, vcc
	global_store_dwordx4 v[202:203], v[198:201], off
	v_cvt_f32_f16_e32 v204, v196
	v_cvt_f32_f16_sdwa v205, v196 dst_sel:DWORD dst_unused:UNUSED_PAD src0_sel:WORD_1
; __device__ __forceinline__ u32x2 f32x4_to_h4(f32x4 v) { return __builtin_bit_cast(u32x2, __builtin_convertvector(v, f16x4)); }
; __device__ __forceinline__ f32x4 h4_to_f32x4(u32x2 v) { return __builtin_convertvector(__builtin_bit_cast(f16x4, v), f32x4); }
;     __device__ __forceinline__ void operator()(const f32x4 (&acc)[2][2][4][2], const pg8::Unit& u, int wr, int wc, int fr, int fq) const {
;     ...
;                     for (int bj = 0; bj < 2; ++bj) { const size_t ro = (size_t)(ai * 128 + m * 16) * D + bj * 128; const u32x4 hv = hb[ai][m][bj];
;                         const f32x4 v0 = h4_to_f32x4((u32x2){hv.x, hv.y}) + gvv[bj][0] * acc[ai][bj][m][0], v1 = h4_to_f32x4((u32x2){hv.z, hv.w}) + gvv[bj][1] * acc[ai][bj][m][1];
;                         if constexpr (OUT_F32) { *(f32x4*)((float*)out + oo + ro) = v0; *(f32x4*)((float*)out + oo + ro + 4) = v1; }
;                         else { const u32x2 h0 = f32x4_to_h4(v0), h1 = f32x4_to_h4(v1); *(u32x4*)((_Float16*)out + oo + ro) = (u32x4){h0.x, h0.y, h1.x, h1.y}; } }
	v_cvt_f32_f16_e32 v198, v195
	v_cvt_f32_f16_sdwa v199, v195 dst_sel:DWORD dst_unused:UNUSED_PAD src0_sel:WORD_1
	v_cvt_f32_f16_e32 v200, v194
	v_cvt_f32_f16_sdwa v201, v194 dst_sel:DWORD dst_unused:UNUSED_PAD src0_sel:WORD_1
	v_pk_fma_f32 v[204:205], v[90:91], v[130:131], v[204:205]
	v_pk_fma_f32 v[194:195], v[100:101], v[136:137], v[198:199]
	v_cvt_f32_f16_e32 v198, v197
	v_cvt_f32_f16_sdwa v199, v197 dst_sel:DWORD dst_unused:UNUSED_PAD src0_sel:WORD_1
	v_pk_fma_f32 v[200:201], v[98:99], v[134:135], v[200:201]
	v_cvt_pk_f16_f32 v195, v194, v195
	v_cvt_pk_f16_f32 v194, v200, v201
	v_pk_fma_f32 v[196:197], v[92:93], v[132:133], v[198:199]
	v_cvt_f32_f16_e32 v198, v192
	v_cvt_pk_f16_f32 v197, v196, v197
	v_cvt_pk_f16_f32 v196, v204, v205
	global_store_dwordx4 v[202:203], v[194:197], off offset:256
	v_cvt_f32_f16_sdwa v199, v192 dst_sel:DWORD dst_unused:UNUSED_PAD src0_sel:WORD_1
	v_pk_fma_f32 v[198:199], v[94:95], v[138:139], v[198:199]
	v_cvt_f32_f16_e32 v194, v191
	v_cvt_f32_f16_sdwa v195, v191 dst_sel:DWORD dst_unused:UNUSED_PAD src0_sel:WORD_1
	v_cvt_f32_f16_e32 v196, v190
	v_cvt_f32_f16_sdwa v197, v190 dst_sel:DWORD dst_unused:UNUSED_PAD src0_sel:WORD_1
	v_pk_fma_f32 v[190:191], v[104:105], v[144:145], v[194:195]
	v_cvt_f32_f16_e32 v194, v193
	v_cvt_f32_f16_sdwa v195, v193 dst_sel:DWORD dst_unused:UNUSED_PAD src0_sel:WORD_1
	v_pk_fma_f32 v[196:197], v[102:103], v[142:143], v[196:197]
	v_cvt_pk_f16_f32 v191, v190, v191
	v_cvt_pk_f16_f32 v190, v196, v197
	v_pk_fma_f32 v[192:193], v[96:97], v[140:141], v[194:195]
	v_add_co_u32_e32 v194, vcc, s49, v226
	v_cvt_pk_f16_f32 v193, v192, v193
	v_cvt_pk_f16_f32 v192, v198, v199
	v_addc_co_u32_e32 v195, vcc, 0, v227, vcc
	global_store_dwordx4 v[194:195], v[190:193], off
	v_cvt_f32_f16_e32 v196, v188
	v_cvt_f32_f16_sdwa v197, v188 dst_sel:DWORD dst_unused:UNUSED_PAD src0_sel:WORD_1
	v_cvt_f32_f16_e32 v190, v187
	v_cvt_f32_f16_sdwa v191, v187 dst_sel:DWORD dst_unused:UNUSED_PAD src0_sel:WORD_1
	v_cvt_f32_f16_e32 v192, v186
	v_cvt_f32_f16_sdwa v193, v186 dst_sel:DWORD dst_unused:UNUSED_PAD src0_sel:WORD_1
	v_pk_fma_f32 v[196:197], v[74:75], v[130:131], v[196:197]
	v_pk_fma_f32 v[186:187], v[84:85], v[136:137], v[190:191]
	v_cvt_f32_f16_e32 v190, v189
	v_cvt_f32_f16_sdwa v191, v189 dst_sel:DWORD dst_unused:UNUSED_PAD src0_sel:WORD_1
	v_pk_fma_f32 v[192:193], v[82:83], v[134:135], v[192:193]
	v_cvt_pk_f16_f32 v187, v186, v187
	v_cvt_pk_f16_f32 v186, v192, v193
	v_pk_fma_f32 v[188:189], v[76:77], v[132:133], v[190:191]
	v_cvt_f32_f16_e32 v190, v184
	v_cvt_pk_f16_f32 v189, v188, v189
	v_cvt_pk_f16_f32 v188, v196, v197
	global_store_dwordx4 v[194:195], v[186:189], off offset:256
	v_cvt_f32_f16_sdwa v191, v184 dst_sel:DWORD dst_unused:UNUSED_PAD src0_sel:WORD_1
	v_pk_fma_f32 v[190:191], v[78:79], v[138:139], v[190:191]
	v_cvt_f32_f16_e32 v186, v183
	v_cvt_f32_f16_sdwa v187, v183 dst_sel:DWORD dst_unused:UNUSED_PAD src0_sel:WORD_1
	v_cvt_f32_f16_e32 v188, v182
	v_cvt_f32_f16_sdwa v189, v182 dst_sel:DWORD dst_unused:UNUSED_PAD src0_sel:WORD_1
	v_pk_fma_f32 v[182:183], v[88:89], v[144:145], v[186:187]
	v_cvt_f32_f16_e32 v186, v185
	v_cvt_f32_f16_sdwa v187, v185 dst_sel:DWORD dst_unused:UNUSED_PAD src0_sel:WORD_1
	v_pk_fma_f32 v[188:189], v[86:87], v[142:143], v[188:189]
	v_cvt_pk_f16_f32 v183, v182, v183
	v_cvt_pk_f16_f32 v182, v188, v189
	v_pk_fma_f32 v[184:185], v[80:81], v[140:141], v[186:187]
	v_add_co_u32_e32 v186, vcc, s46, v226
	v_cvt_pk_f16_f32 v185, v184, v185
	v_cvt_pk_f16_f32 v184, v190, v191
	v_addc_co_u32_e32 v187, vcc, 0, v227, vcc
	global_store_dwordx4 v[186:187], v[182:185], off
	v_cvt_f32_f16_e32 v188, v180
	v_cvt_f32_f16_sdwa v189, v180 dst_sel:DWORD dst_unused:UNUSED_PAD src0_sel:WORD_1
	v_cvt_f32_f16_e32 v182, v179
	v_cvt_f32_f16_sdwa v183, v179 dst_sel:DWORD dst_unused:UNUSED_PAD src0_sel:WORD_1
	v_cvt_f32_f16_e32 v184, v178
	v_cvt_f32_f16_sdwa v185, v178 dst_sel:DWORD dst_unused:UNUSED_PAD src0_sel:WORD_1
	v_pk_fma_f32 v[188:189], v[66:67], v[130:131], v[188:189]
	v_pk_fma_f32 v[178:179], v[72:73], v[136:137], v[182:183]
	v_cvt_f32_f16_e32 v182, v181
	v_cvt_f32_f16_sdwa v183, v181 dst_sel:DWORD dst_unused:UNUSED_PAD src0_sel:WORD_1
	v_pk_fma_f32 v[184:185], v[70:71], v[134:135], v[184:185]
	v_cvt_pk_f16_f32 v179, v178, v179
	v_cvt_pk_f16_f32 v178, v184, v185
	v_pk_fma_f32 v[180:181], v[68:69], v[132:133], v[182:183]
	v_cvt_f32_f16_e32 v182, v176
	v_cvt_pk_f16_f32 v181, v180, v181
	v_cvt_pk_f16_f32 v180, v188, v189
	global_store_dwordx4 v[186:187], v[178:181], off offset:256
	v_cvt_f32_f16_sdwa v183, v176 dst_sel:DWORD dst_unused:UNUSED_PAD src0_sel:WORD_1
	v_pk_fma_f32 v[182:183], v[58:59], v[138:139], v[182:183]
	v_cvt_f32_f16_e32 v178, v175
	v_cvt_f32_f16_sdwa v179, v175 dst_sel:DWORD dst_unused:UNUSED_PAD src0_sel:WORD_1
	v_cvt_f32_f16_e32 v180, v174
	v_cvt_f32_f16_sdwa v181, v174 dst_sel:DWORD dst_unused:UNUSED_PAD src0_sel:WORD_1
	v_pk_fma_f32 v[174:175], v[64:65], v[144:145], v[178:179]
	v_cvt_f32_f16_e32 v178, v177
	v_cvt_f32_f16_sdwa v179, v177 dst_sel:DWORD dst_unused:UNUSED_PAD src0_sel:WORD_1
	v_pk_fma_f32 v[180:181], v[62:63], v[142:143], v[180:181]
	v_cvt_pk_f16_f32 v175, v174, v175
	v_cvt_pk_f16_f32 v174, v180, v181
	v_pk_fma_f32 v[176:177], v[60:61], v[140:141], v[178:179]
	v_add_co_u32_e32 v178, vcc, s50, v226
	v_cvt_pk_f16_f32 v177, v176, v177
	v_cvt_pk_f16_f32 v176, v182, v183
	v_addc_co_u32_e32 v179, vcc, 0, v227, vcc
	global_store_dwordx4 v[178:179], v[174:177], off
	v_cvt_f32_f16_e32 v180, v172
	v_cvt_f32_f16_sdwa v181, v172 dst_sel:DWORD dst_unused:UNUSED_PAD src0_sel:WORD_1
	v_cvt_f32_f16_e32 v174, v171
	v_cvt_f32_f16_sdwa v175, v171 dst_sel:DWORD dst_unused:UNUSED_PAD src0_sel:WORD_1
	v_cvt_f32_f16_e32 v176, v170
	v_cvt_f32_f16_sdwa v177, v170 dst_sel:DWORD dst_unused:UNUSED_PAD src0_sel:WORD_1
	v_pk_fma_f32 v[180:181], v[42:43], v[130:131], v[180:181]
	v_pk_fma_f32 v[170:171], v[52:53], v[136:137], v[174:175]
	v_cvt_f32_f16_e32 v174, v173
	v_cvt_f32_f16_sdwa v175, v173 dst_sel:DWORD dst_unused:UNUSED_PAD src0_sel:WORD_1
	v_pk_fma_f32 v[176:177], v[50:51], v[134:135], v[176:177]
	v_cvt_pk_f16_f32 v171, v170, v171
	v_cvt_pk_f16_f32 v170, v176, v177
	v_pk_fma_f32 v[172:173], v[44:45], v[132:133], v[174:175]
	s_waitcnt vmcnt(14)
; __device__ __forceinline__ u32x2 f32x4_to_h4(f32x4 v) { return __builtin_bit_cast(u32x2, __builtin_convertvector(v, f16x4)); }
; __device__ __forceinline__ f32x4 h4_to_f32x4(u32x2 v) { return __builtin_convertvector(__builtin_bit_cast(f16x4, v), f32x4); }
;     __device__ __forceinline__ void operator()(const f32x4 (&acc)[2][2][4][2], const pg8::Unit& u, int wr, int wc, int fr, int fq) const {
;     ...
;                     for (int bj = 0; bj < 2; ++bj) { const size_t ro = (size_t)(ai * 128 + m * 16) * D + bj * 128; const u32x4 hv = hb[ai][m][bj];
;                         const f32x4 v0 = h4_to_f32x4((u32x2){hv.x, hv.y}) + gvv[bj][0] * acc[ai][bj][m][0], v1 = h4_to_f32x4((u32x2){hv.z, hv.w}) + gvv[bj][1] * acc[ai][bj][m][1];
;                         if constexpr (OUT_F32) { *(f32x4*)((float*)out + oo + ro) = v0; *(f32x4*)((float*)out + oo + ro + 4) = v1; }
;                         else { const u32x2 h0 = f32x4_to_h4(v0), h1 = f32x4_to_h4(v1); *(u32x4*)((_Float16*)out + oo + ro) = (u32x4){h0.x, h0.y, h1.x, h1.y}; } }
	v_cvt_f32_f16_e32 v174, v168
	v_cvt_pk_f16_f32 v173, v172, v173
	v_cvt_pk_f16_f32 v172, v180, v181
	global_store_dwordx4 v[178:179], v[170:173], off offset:256
	v_cvt_f32_f16_sdwa v175, v168 dst_sel:DWORD dst_unused:UNUSED_PAD src0_sel:WORD_1
	v_pk_fma_f32 v[174:175], v[46:47], v[138:139], v[174:175]
	v_cvt_f32_f16_e32 v170, v167
	v_cvt_f32_f16_sdwa v171, v167 dst_sel:DWORD dst_unused:UNUSED_PAD src0_sel:WORD_1
	v_cvt_f32_f16_e32 v172, v166
	v_cvt_f32_f16_sdwa v173, v166 dst_sel:DWORD dst_unused:UNUSED_PAD src0_sel:WORD_1
	v_pk_fma_f32 v[166:167], v[56:57], v[144:145], v[170:171]
	v_cvt_f32_f16_e32 v170, v169
	v_cvt_f32_f16_sdwa v171, v169 dst_sel:DWORD dst_unused:UNUSED_PAD src0_sel:WORD_1
	v_pk_fma_f32 v[172:173], v[54:55], v[142:143], v[172:173]
	v_cvt_pk_f16_f32 v167, v166, v167
	v_cvt_pk_f16_f32 v166, v172, v173
	v_pk_fma_f32 v[168:169], v[48:49], v[140:141], v[170:171]
	v_add_co_u32_e32 v170, vcc, s51, v226
	v_cvt_pk_f16_f32 v169, v168, v169
	v_cvt_pk_f16_f32 v168, v174, v175
	v_addc_co_u32_e32 v171, vcc, 0, v227, vcc
	global_store_dwordx4 v[170:171], v[166:169], off
	s_waitcnt vmcnt(15)
	v_cvt_f32_f16_e32 v172, v164
	v_cvt_f32_f16_sdwa v173, v164 dst_sel:DWORD dst_unused:UNUSED_PAD src0_sel:WORD_1
	v_cvt_f32_f16_e32 v166, v163
	v_cvt_f32_f16_sdwa v167, v163 dst_sel:DWORD dst_unused:UNUSED_PAD src0_sel:WORD_1
	v_cvt_f32_f16_e32 v168, v162
	v_cvt_f32_f16_sdwa v169, v162 dst_sel:DWORD dst_unused:UNUSED_PAD src0_sel:WORD_1
	v_pk_fma_f32 v[172:173], v[26:27], v[130:131], v[172:173]
	v_pk_fma_f32 v[162:163], v[36:37], v[136:137], v[166:167]
	v_cvt_f32_f16_e32 v166, v165
	v_cvt_f32_f16_sdwa v167, v165 dst_sel:DWORD dst_unused:UNUSED_PAD src0_sel:WORD_1
	v_pk_fma_f32 v[168:169], v[34:35], v[134:135], v[168:169]
	v_cvt_pk_f16_f32 v163, v162, v163
	v_cvt_pk_f16_f32 v162, v168, v169
	v_pk_fma_f32 v[164:165], v[28:29], v[132:133], v[166:167]
	s_waitcnt vmcnt(14)
	v_cvt_f32_f16_e32 v166, v160
	v_cvt_pk_f16_f32 v165, v164, v165
	v_cvt_pk_f16_f32 v164, v172, v173
	global_store_dwordx4 v[170:171], v[162:165], off offset:256
	v_cvt_f32_f16_sdwa v167, v160 dst_sel:DWORD dst_unused:UNUSED_PAD src0_sel:WORD_1
	v_pk_fma_f32 v[166:167], v[30:31], v[138:139], v[166:167]
	v_cvt_f32_f16_e32 v162, v159
	v_cvt_f32_f16_sdwa v163, v159 dst_sel:DWORD dst_unused:UNUSED_PAD src0_sel:WORD_1
	v_cvt_f32_f16_e32 v164, v158
	v_cvt_f32_f16_sdwa v165, v158 dst_sel:DWORD dst_unused:UNUSED_PAD src0_sel:WORD_1
	v_pk_fma_f32 v[158:159], v[40:41], v[144:145], v[162:163]
	v_cvt_f32_f16_e32 v162, v161
	v_cvt_f32_f16_sdwa v163, v161 dst_sel:DWORD dst_unused:UNUSED_PAD src0_sel:WORD_1
	v_pk_fma_f32 v[164:165], v[38:39], v[142:143], v[164:165]
	v_cvt_pk_f16_f32 v159, v158, v159
	v_cvt_pk_f16_f32 v158, v164, v165
	v_pk_fma_f32 v[160:161], v[32:33], v[140:141], v[162:163]
	v_add_co_u32_e32 v162, vcc, s68, v226
	v_cvt_pk_f16_f32 v161, v160, v161
	v_cvt_pk_f16_f32 v160, v166, v167
	v_addc_co_u32_e32 v163, vcc, 0, v227, vcc
	global_store_dwordx4 v[162:163], v[158:161], off
	s_waitcnt vmcnt(15)
	v_cvt_f32_f16_e32 v164, v156
	v_cvt_f32_f16_sdwa v165, v156 dst_sel:DWORD dst_unused:UNUSED_PAD src0_sel:WORD_1
	v_cvt_f32_f16_e32 v158, v155
	v_cvt_f32_f16_sdwa v159, v155 dst_sel:DWORD dst_unused:UNUSED_PAD src0_sel:WORD_1
	v_cvt_f32_f16_e32 v160, v154
	v_cvt_f32_f16_sdwa v161, v154 dst_sel:DWORD dst_unused:UNUSED_PAD src0_sel:WORD_1
	v_pk_fma_f32 v[164:165], v[10:11], v[130:131], v[164:165]
	v_pk_fma_f32 v[154:155], v[20:21], v[136:137], v[158:159]
	v_cvt_f32_f16_e32 v158, v157
	v_cvt_f32_f16_sdwa v159, v157 dst_sel:DWORD dst_unused:UNUSED_PAD src0_sel:WORD_1
	v_pk_fma_f32 v[160:161], v[18:19], v[134:135], v[160:161]
	v_cvt_pk_f16_f32 v155, v154, v155
	v_cvt_pk_f16_f32 v154, v160, v161
	v_pk_fma_f32 v[156:157], v[12:13], v[132:133], v[158:159]
	s_waitcnt vmcnt(14)
	v_cvt_f32_f16_e32 v158, v152
	v_cvt_pk_f16_f32 v157, v156, v157
	v_cvt_pk_f16_f32 v156, v164, v165
	global_store_dwordx4 v[162:163], v[154:157], off offset:256
	v_cvt_f32_f16_sdwa v159, v152 dst_sel:DWORD dst_unused:UNUSED_PAD src0_sel:WORD_1
	v_pk_fma_f32 v[158:159], v[14:15], v[138:139], v[158:159]
	v_cvt_f32_f16_e32 v154, v151
	v_cvt_f32_f16_sdwa v155, v151 dst_sel:DWORD dst_unused:UNUSED_PAD src0_sel:WORD_1
	v_cvt_f32_f16_e32 v156, v150
	v_cvt_f32_f16_sdwa v157, v150 dst_sel:DWORD dst_unused:UNUSED_PAD src0_sel:WORD_1
	v_pk_fma_f32 v[150:151], v[24:25], v[144:145], v[154:155]
	v_cvt_f32_f16_e32 v154, v153
	v_cvt_f32_f16_sdwa v155, v153 dst_sel:DWORD dst_unused:UNUSED_PAD src0_sel:WORD_1
	v_pk_fma_f32 v[156:157], v[22:23], v[142:143], v[156:157]
	v_cvt_pk_f16_f32 v151, v150, v151
	v_cvt_pk_f16_f32 v150, v156, v157
	v_pk_fma_f32 v[152:153], v[16:17], v[140:141], v[154:155]
	v_add_co_u32_e32 v154, vcc, s69, v226
	v_cvt_pk_f16_f32 v153, v152, v153
	v_cvt_pk_f16_f32 v152, v158, v159
	v_addc_co_u32_e32 v155, vcc, 0, v227, vcc
	global_store_dwordx4 v[154:155], v[150:153], off
	s_waitcnt vmcnt(15)
	v_cvt_f32_f16_e32 v156, v148
	v_cvt_f32_f16_sdwa v157, v148 dst_sel:DWORD dst_unused:UNUSED_PAD src0_sel:WORD_1
	v_cvt_f32_f16_e32 v150, v147
	v_cvt_f32_f16_sdwa v151, v147 dst_sel:DWORD dst_unused:UNUSED_PAD src0_sel:WORD_1
	v_cvt_f32_f16_e32 v152, v146
	v_cvt_f32_f16_sdwa v153, v146 dst_sel:DWORD dst_unused:UNUSED_PAD src0_sel:WORD_1
	v_pk_fma_f32 v[156:157], v[2:3], v[130:131], v[156:157]
	v_pk_fma_f32 v[146:147], v[8:9], v[136:137], v[150:151]
	v_cvt_f32_f16_e32 v150, v149
	v_cvt_f32_f16_sdwa v151, v149 dst_sel:DWORD dst_unused:UNUSED_PAD src0_sel:WORD_1
	v_pk_fma_f32 v[152:153], v[6:7], v[134:135], v[152:153]
	v_cvt_pk_f16_f32 v147, v146, v147
	v_cvt_pk_f16_f32 v146, v152, v153
	v_pk_fma_f32 v[148:149], v[4:5], v[132:133], v[150:151]
	s_nop 0
	v_cvt_pk_f16_f32 v149, v148, v149
	v_cvt_pk_f16_f32 v148, v156, v157
	global_store_dwordx4 v[154:155], v[146:149], off offset:256

;     __device__ __forceinline__ void operator()(const f32x4 (&acc)[2][2][4][2], const pg8::Unit& u, int wr, int wc, int fr, int fq) const {
;         const float coef = __builtin_bit_cast(float, __builtin_amdgcn_readfirstlane(__builtin_bit_cast(int, this->coef)));
;         GAS float* const part = (GAS float*)(((unsigned long long)(unsigned)__builtin_amdgcn_readfirstlane((int)((unsigned long long)this->part >> 32)) << 32) | (unsigned)__builtin_amdgcn_readfirstlane((int)(unsigned long long)this->part));
;         const int row0 = u.pm * 256 + wr * 64 + fr, col0 = u.pn * 256 + wc * 32 + 8 * fq;
;         const int r = u.pm < 64 ? (u.pm >> 3) : 8;
;         const float* gv = gate + (size_t)r * DMODW + col0;
;         f32x4 gvv[2][2];
; #pragma unroll
;         for (int bj = 0; bj < 2; ++bj)
; #pragma unroll
;             for (int n = 0; n < 2; ++n) gvv[bj][n] = *(const f32x4*)(gv + bj * 128 + 4 * n) * coef;
;         if (u.kind >= 2) {
;             GAS float* op = part + (size_t)(u.kind - 2) * (PART_STRIDE / 4) + (size_t)(row0 - M_LAT) * D + col0;
; #pragma unroll
;             for (int ai = 0; ai < 2; ++ai)
; #pragma unroll
;                 for (int m = 0; m < 4; ++m) { const size_t ro = (size_t)(ai * 128 + m * 16) * D;
; #pragma unroll
;                     for (int bj = 0; bj < 2; ++bj)
; #pragma unroll
;                         for (int n = 0; n < 2; ++n) *(GAS f32x4*)(op + ro + bj * 128 + 4 * n) = gvv[bj][n] * acc[ai][bj][m][n]; }
;             return;
;         }
;         const size_t eo = (u.pm < 64 ? (size_t)row0 : (size_t)(row0 - M_LAT)) * D + col0;
;         const void* bsel = u.pm < 64 ? base_lat : base_ctx;
;         const size_t oo = (size_t)row0 * D + col0;
;         if constexpr (!BASE_F32) {
;             u32x4 hb[2][4][2];
; #pragma unroll
;             for (int ai = 0; ai < 2; ++ai)
; #pragma unroll
;                 for (int m = 0; m < 4; ++m)
; #pragma unroll
;                     for (int bj = 0; bj < 2; ++bj) hb[ai][m][bj] = *(const u32x4*)((const _Float16*)bsel + eo + (size_t)(ai * 128 + m * 16) * D + bj * 128);
; #pragma unroll
;             for (int ai = 0; ai < 2; ++ai)
; #pragma unroll
;                 for (int m = 0; m < 4; ++m)
; #pragma unroll
;                     for (int bj = 0; bj < 2; ++bj) { const size_t ro = (size_t)(ai * 128 + m * 16) * D + bj * 128; const u32x4 hv = hb[ai][m][bj];
.LBB0_1309:
	s_lshl_b64 s[18:19], s[18:19], 2
	v_lshl_or_b32 v224, s69, 8, v232
	s_add_u32 s18, s34, s18
	s_addc_u32 s19, s35, s19
	v_ashrrev_i32_e32 v225, 31, v224
	v_lshl_add_u64 v[10:11], v[224:225], 2, s[18:19]
	global_load_dwordx4 v[2:5], v[10:11], off offset:16
	global_load_dwordx4 v[6:9], v[10:11], off
	v_lshl_add_u32 v222, s70, 8, v230
	s_mov_b64 s[18:19], -1
	s_cmp_lt_i32 s49, 2
	v_ashrrev_i32_e32 v223, 31, v222
	s_waitcnt vmcnt(0)
	v_pk_mul_f32 v[206:207], v[4:5], s[12:13] op_sel_hi:[1,0]
	v_pk_mul_f32 v[210:211], v[8:9], s[12:13] op_sel_hi:[1,0]
	v_pk_mul_f32 v[212:213], v[6:7], s[12:13] op_sel_hi:[1,0]
	v_pk_mul_f32 v[208:209], v[2:3], s[12:13] op_sel_hi:[1,0]
	global_load_dwordx4 v[2:5], v[10:11], off offset:528
	global_load_dwordx4 v[6:9], v[10:11], off offset:512
	s_waitcnt vmcnt(1)
	v_pk_mul_f32 v[214:215], v[4:5], s[12:13] op_sel_hi:[1,0]
	s_waitcnt vmcnt(0)
	v_pk_mul_f32 v[218:219], v[8:9], s[12:13] op_sel_hi:[1,0]
	v_pk_mul_f32 v[220:221], v[6:7], s[12:13] op_sel_hi:[1,0]
	v_pk_mul_f32 v[216:217], v[2:3], s[12:13] op_sel_hi:[1,0]
	s_cbranch_scc0 .LBB0_1312
	v_add_u32_e32 v2, 0xffffc000, v222
	v_cndmask_b32_e32 v2, v2, v222, vcc
	v_readlane_b32 s20, v253, 52
	v_ashrrev_i32_e32 v3, 31, v2
	s_and_b64 s[18:19], vcc, exec
	v_readlane_b32 s21, v253, 53
	s_cselect_b32 s19, s21, s33
	s_cselect_b32 s18, s20, s31
	v_lshlrev_b64 v[2:3], 12, v[2:3]
	v_lshl_add_u64 v[2:3], s[18:19], 0, v[2:3]
	v_lshlrev_b64 v[226:227], 1, v[224:225]
	v_lshl_add_u64 v[2:3], v[2:3], 0, v[226:227]
	global_load_dwordx4 v[236:239], v[2:3], off nt
	global_load_dwordx4 v[186:189], v[2:3], off offset:256 nt
	v_add_co_u32_e32 v4, vcc, s30, v2
	v_lshlrev_b64 v[240:241], 12, v[222:223]
	s_nop 0
	v_addc_co_u32_e32 v5, vcc, 0, v3, vcc
	global_load_dwordx4 v[182:185], v[4:5], off nt
	global_load_dwordx4 v[178:181], v[4:5], off offset:256 nt
	v_add_co_u32_e32 v4, vcc, s42, v2
	v_lshl_add_u64 v[240:241], s[20:21], 0, v[240:241]
	s_nop 0
	v_addc_co_u32_e32 v5, vcc, 0, v3, vcc
	global_load_dwordx4 v[174:177], v[4:5], off nt
	global_load_dwordx4 v[170:173], v[4:5], off offset:256 nt
	v_add_co_u32_e32 v4, vcc, s43, v2
	v_lshl_add_u64 v[226:227], v[240:241], 0, v[226:227]
	s_nop 0
	v_addc_co_u32_e32 v5, vcc, 0, v3, vcc
	global_load_dwordx4 v[166:169], v[4:5], off nt
	global_load_dwordx4 v[162:165], v[4:5], off offset:256 nt
	v_add_co_u32_e32 v4, vcc, s44, v2
	s_nop 1
	v_addc_co_u32_e32 v5, vcc, 0, v3, vcc
	global_load_dwordx4 v[30:33], v[4:5], off nt
	global_load_dwordx4 v[26:29], v[4:5], off offset:256 nt
	v_add_co_u32_e32 v4, vcc, s45, v2
	s_waitcnt vmcnt(9)
	v_cvt_f32_f16_e32 v242, v237
	v_cvt_f32_f16_sdwa v243, v237 dst_sel:DWORD dst_unused:UNUSED_PAD src0_sel:WORD_1
	v_cvt_f32_f16_e32 v244, v236
	v_cvt_f32_f16_sdwa v245, v236 dst_sel:DWORD dst_unused:UNUSED_PAD src0_sel:WORD_1
	v_cvt_f32_f16_e32 v246, v238
	v_pk_fma_f32 v[236:237], v[160:161], v[210:211], v[242:243]
	v_cvt_f32_f16_e32 v242, v239
	v_cvt_f32_f16_sdwa v243, v239 dst_sel:DWORD dst_unused:UNUSED_PAD src0_sel:WORD_1
	v_cvt_f32_f16_sdwa v247, v238 dst_sel:DWORD dst_unused:UNUSED_PAD src0_sel:WORD_1
	v_addc_co_u32_e32 v5, vcc, 0, v3, vcc
	global_load_dwordx4 v[22:25], v[4:5], off nt
	global_load_dwordx4 v[18:21], v[4:5], off offset:256 nt
	v_add_co_u32_e32 v4, vcc, s46, v2
	v_pk_fma_f32 v[244:245], v[158:159], v[212:213], v[244:245]
	s_nop 0
	v_addc_co_u32_e32 v5, vcc, 0, v3, vcc
	v_add_co_u32_e32 v2, vcc, s47, v2
	v_pk_fma_f32 v[246:247], v[154:155], v[208:209], v[246:247]
	v_pk_fma_f32 v[238:239], v[156:157], v[206:207], v[242:243]
	v_addc_co_u32_e32 v3, vcc, 0, v3, vcc
	v_cvt_pk_f16_f32 v237, v236, v237
	v_cvt_pk_f16_f32 v236, v244, v245
	v_cvt_pk_f16_f32 v239, v238, v239
	v_cvt_pk_f16_f32 v238, v246, v247
	global_load_dwordx4 v[14:17], v[4:5], off nt
	global_load_dwordx4 v[10:13], v[4:5], off offset:256 nt
	global_load_dwordx4 v[6:9], v[2:3], off nt
	s_nop 0
	global_load_dwordx4 v[2:5], v[2:3], off offset:256 nt
	s_waitcnt vmcnt(14)
	v_cvt_f32_f16_e32 v240, v188
	global_store_dwordx4 v[226:227], v[236:239], off
	v_cvt_f32_f16_sdwa v241, v188 dst_sel:DWORD dst_unused:UNUSED_PAD src0_sel:WORD_1
	v_pk_fma_f32 v[240:241], v[138:139], v[216:217], v[240:241]
	v_cvt_f32_f16_e32 v236, v187
	v_cvt_f32_f16_sdwa v237, v187 dst_sel:DWORD dst_unused:UNUSED_PAD src0_sel:WORD_1
	v_cvt_f32_f16_e32 v238, v186
	v_cvt_f32_f16_sdwa v239, v186 dst_sel:DWORD dst_unused:UNUSED_PAD src0_sel:WORD_1
	v_pk_fma_f32 v[186:187], v[148:149], v[218:219], v[236:237]
	v_cvt_f32_f16_e32 v236, v189
	v_cvt_f32_f16_sdwa v237, v189 dst_sel:DWORD dst_unused:UNUSED_PAD src0_sel:WORD_1
	v_pk_fma_f32 v[238:239], v[146:147], v[220:221], v[238:239]
	v_cvt_pk_f16_f32 v187, v186, v187
	v_cvt_pk_f16_f32 v186, v238, v239
	v_pk_fma_f32 v[188:189], v[140:141], v[214:215], v[236:237]
	s_waitcnt vmcnt(14)
	v_cvt_f32_f16_e32 v236, v184
	v_cvt_pk_f16_f32 v189, v188, v189
	v_cvt_pk_f16_f32 v188, v240, v241
	global_store_dwordx4 v[226:227], v[186:189], off offset:256
	v_cvt_f32_f16_sdwa v237, v184 dst_sel:DWORD dst_unused:UNUSED_PAD src0_sel:WORD_1
	v_pk_fma_f32 v[236:237], v[142:143], v[208:209], v[236:237]
	v_cvt_f32_f16_e32 v186, v183
	v_cvt_f32_f16_sdwa v187, v183 dst_sel:DWORD dst_unused:UNUSED_PAD src0_sel:WORD_1
	v_cvt_f32_f16_e32 v188, v182
	v_cvt_f32_f16_sdwa v189, v182 dst_sel:DWORD dst_unused:UNUSED_PAD src0_sel:WORD_1
	v_pk_fma_f32 v[182:183], v[152:153], v[210:211], v[186:187]
	v_cvt_f32_f16_e32 v186, v185
	v_cvt_f32_f16_sdwa v187, v185 dst_sel:DWORD dst_unused:UNUSED_PAD src0_sel:WORD_1
	v_pk_fma_f32 v[188:189], v[150:151], v[212:213], v[188:189]
	v_cvt_pk_f16_f32 v183, v182, v183
	v_cvt_pk_f16_f32 v182, v188, v189
	v_pk_fma_f32 v[184:185], v[144:145], v[206:207], v[186:187]
	v_add_co_u32_e32 v186, vcc, s30, v226
	v_cvt_pk_f16_f32 v185, v184, v185
	v_cvt_pk_f16_f32 v184, v236, v237
	v_addc_co_u32_e32 v187, vcc, 0, v227, vcc
	global_store_dwordx4 v[186:187], v[182:185], off
	s_waitcnt vmcnt(15)
; __device__ __forceinline__ u32x2 f32x4_to_h4(f32x4 v) { return __builtin_bit_cast(u32x2, __builtin_convertvector(v, f16x4)); }
; __device__ __forceinline__ f32x4 h4_to_f32x4(u32x2 v) { return __builtin_convertvector(__builtin_bit_cast(f16x4, v), f32x4); }
;     __device__ __forceinline__ void operator()(const f32x4 (&acc)[2][2][4][2], const pg8::Unit& u, int wr, int wc, int fr, int fq) const {
;     ...
;                     for (int bj = 0; bj < 2; ++bj) { const size_t ro = (size_t)(ai * 128 + m * 16) * D + bj * 128; const u32x4 hv = hb[ai][m][bj];
;                         const f32x4 v0 = h4_to_f32x4((u32x2){hv.x, hv.y}) + gvv[bj][0] * acc[ai][bj][m][0], v1 = h4_to_f32x4((u32x2){hv.z, hv.w}) + gvv[bj][1] * acc[ai][bj][m][1];
;                         if constexpr (OUT_F32) { *(f32x4*)((float*)out + oo + ro) = v0; *(f32x4*)((float*)out + oo + ro + 4) = v1; }
;                         else { const u32x2 h0 = f32x4_to_h4(v0), h1 = f32x4_to_h4(v1); *(u32x4*)((_Float16*)out + oo + ro) = (u32x4){h0.x, h0.y, h1.x, h1.y}; } }
	v_cvt_f32_f16_e32 v188, v180
	v_cvt_f32_f16_sdwa v189, v180 dst_sel:DWORD dst_unused:UNUSED_PAD src0_sel:WORD_1
	v_cvt_f32_f16_e32 v182, v179
	v_cvt_f32_f16_sdwa v183, v179 dst_sel:DWORD dst_unused:UNUSED_PAD src0_sel:WORD_1
	v_cvt_f32_f16_e32 v184, v178
	v_cvt_f32_f16_sdwa v185, v178 dst_sel:DWORD dst_unused:UNUSED_PAD src0_sel:WORD_1
	v_pk_fma_f32 v[188:189], v[122:123], v[216:217], v[188:189]
	v_pk_fma_f32 v[178:179], v[132:133], v[218:219], v[182:183]
	v_cvt_f32_f16_e32 v182, v181
	v_cvt_f32_f16_sdwa v183, v181 dst_sel:DWORD dst_unused:UNUSED_PAD src0_sel:WORD_1
	v_pk_fma_f32 v[184:185], v[130:131], v[220:221], v[184:185]
	v_cvt_pk_f16_f32 v179, v178, v179
	v_cvt_pk_f16_f32 v178, v184, v185
	v_pk_fma_f32 v[180:181], v[124:125], v[214:215], v[182:183]
	s_waitcnt vmcnt(14)
	v_cvt_f32_f16_e32 v182, v176
	v_cvt_pk_f16_f32 v181, v180, v181
	v_cvt_pk_f16_f32 v180, v188, v189
	global_store_dwordx4 v[186:187], v[178:181], off offset:256
	v_cvt_f32_f16_sdwa v183, v176 dst_sel:DWORD dst_unused:UNUSED_PAD src0_sel:WORD_1
	v_pk_fma_f32 v[182:183], v[126:127], v[208:209], v[182:183]
	v_cvt_f32_f16_e32 v178, v175
	v_cvt_f32_f16_sdwa v179, v175 dst_sel:DWORD dst_unused:UNUSED_PAD src0_sel:WORD_1
	v_cvt_f32_f16_e32 v180, v174
	v_cvt_f32_f16_sdwa v181, v174 dst_sel:DWORD dst_unused:UNUSED_PAD src0_sel:WORD_1
	v_pk_fma_f32 v[174:175], v[136:137], v[210:211], v[178:179]
	v_cvt_f32_f16_e32 v178, v177
	v_cvt_f32_f16_sdwa v179, v177 dst_sel:DWORD dst_unused:UNUSED_PAD src0_sel:WORD_1
	v_pk_fma_f32 v[180:181], v[134:135], v[212:213], v[180:181]
	v_cvt_pk_f16_f32 v175, v174, v175
	v_cvt_pk_f16_f32 v174, v180, v181
	v_pk_fma_f32 v[176:177], v[128:129], v[206:207], v[178:179]
	v_add_co_u32_e32 v178, vcc, s42, v226
	v_cvt_pk_f16_f32 v177, v176, v177
	v_cvt_pk_f16_f32 v176, v182, v183
	v_addc_co_u32_e32 v179, vcc, 0, v227, vcc
	global_store_dwordx4 v[178:179], v[174:177], off
	s_waitcnt vmcnt(15)
	v_cvt_f32_f16_e32 v180, v172
	v_cvt_f32_f16_sdwa v181, v172 dst_sel:DWORD dst_unused:UNUSED_PAD src0_sel:WORD_1
	v_cvt_f32_f16_e32 v174, v171
	v_cvt_f32_f16_sdwa v175, v171 dst_sel:DWORD dst_unused:UNUSED_PAD src0_sel:WORD_1
	v_cvt_f32_f16_e32 v176, v170
	v_cvt_f32_f16_sdwa v177, v170 dst_sel:DWORD dst_unused:UNUSED_PAD src0_sel:WORD_1
	v_pk_fma_f32 v[180:181], v[106:107], v[216:217], v[180:181]
	v_pk_fma_f32 v[170:171], v[116:117], v[218:219], v[174:175]
	v_cvt_f32_f16_e32 v174, v173
	v_cvt_f32_f16_sdwa v175, v173 dst_sel:DWORD dst_unused:UNUSED_PAD src0_sel:WORD_1
	v_pk_fma_f32 v[176:177], v[114:115], v[220:221], v[176:177]
	v_cvt_pk_f16_f32 v171, v170, v171
	v_cvt_pk_f16_f32 v170, v176, v177
	v_pk_fma_f32 v[172:173], v[108:109], v[214:215], v[174:175]
	s_waitcnt vmcnt(14)
	v_cvt_f32_f16_e32 v174, v168
	v_cvt_pk_f16_f32 v173, v172, v173
	v_cvt_pk_f16_f32 v172, v180, v181
	global_store_dwordx4 v[178:179], v[170:173], off offset:256
	v_cvt_f32_f16_sdwa v175, v168 dst_sel:DWORD dst_unused:UNUSED_PAD src0_sel:WORD_1
	v_pk_fma_f32 v[174:175], v[110:111], v[208:209], v[174:175]
	v_cvt_f32_f16_e32 v170, v167
	v_cvt_f32_f16_sdwa v171, v167 dst_sel:DWORD dst_unused:UNUSED_PAD src0_sel:WORD_1
	v_cvt_f32_f16_e32 v172, v166
	v_cvt_f32_f16_sdwa v173, v166 dst_sel:DWORD dst_unused:UNUSED_PAD src0_sel:WORD_1
	v_pk_fma_f32 v[166:167], v[120:121], v[210:211], v[170:171]
	v_cvt_f32_f16_e32 v170, v169
	v_cvt_f32_f16_sdwa v171, v169 dst_sel:DWORD dst_unused:UNUSED_PAD src0_sel:WORD_1
	v_pk_fma_f32 v[172:173], v[118:119], v[212:213], v[172:173]
	v_cvt_pk_f16_f32 v167, v166, v167
	v_cvt_pk_f16_f32 v166, v172, v173
	v_pk_fma_f32 v[168:169], v[112:113], v[206:207], v[170:171]
	v_add_co_u32_e32 v170, vcc, s43, v226
	v_cvt_pk_f16_f32 v169, v168, v169
	v_cvt_pk_f16_f32 v168, v174, v175
	v_addc_co_u32_e32 v171, vcc, 0, v227, vcc
	global_store_dwordx4 v[170:171], v[166:169], off
	s_waitcnt vmcnt(15)
	v_cvt_f32_f16_e32 v172, v164
	v_cvt_f32_f16_sdwa v173, v164 dst_sel:DWORD dst_unused:UNUSED_PAD src0_sel:WORD_1
	v_cvt_f32_f16_e32 v166, v163
	v_cvt_f32_f16_sdwa v167, v163 dst_sel:DWORD dst_unused:UNUSED_PAD src0_sel:WORD_1
	v_cvt_f32_f16_e32 v168, v162
	v_cvt_f32_f16_sdwa v169, v162 dst_sel:DWORD dst_unused:UNUSED_PAD src0_sel:WORD_1
	v_pk_fma_f32 v[172:173], v[98:99], v[216:217], v[172:173]
	v_pk_fma_f32 v[162:163], v[104:105], v[218:219], v[166:167]
	v_cvt_f32_f16_e32 v166, v165
	v_cvt_f32_f16_sdwa v167, v165 dst_sel:DWORD dst_unused:UNUSED_PAD src0_sel:WORD_1
	v_pk_fma_f32 v[168:169], v[102:103], v[220:221], v[168:169]
	v_cvt_pk_f16_f32 v163, v162, v163
	v_cvt_pk_f16_f32 v162, v168, v169
	v_pk_fma_f32 v[164:165], v[100:101], v[214:215], v[166:167]
	s_waitcnt vmcnt(14)
	v_cvt_f32_f16_e32 v166, v32
	v_cvt_pk_f16_f32 v165, v164, v165
	v_cvt_pk_f16_f32 v164, v172, v173
	global_store_dwordx4 v[170:171], v[162:165], off offset:256
	v_cvt_f32_f16_sdwa v167, v32 dst_sel:DWORD dst_unused:UNUSED_PAD src0_sel:WORD_1
	v_pk_fma_f32 v[166:167], v[90:91], v[208:209], v[166:167]
	v_cvt_f32_f16_e32 v162, v31
	v_cvt_f32_f16_sdwa v163, v31 dst_sel:DWORD dst_unused:UNUSED_PAD src0_sel:WORD_1
	v_cvt_f32_f16_e32 v164, v30
	v_cvt_f32_f16_sdwa v165, v30 dst_sel:DWORD dst_unused:UNUSED_PAD src0_sel:WORD_1
	v_pk_fma_f32 v[30:31], v[96:97], v[210:211], v[162:163]
	v_cvt_f32_f16_e32 v162, v33
	v_cvt_f32_f16_sdwa v163, v33 dst_sel:DWORD dst_unused:UNUSED_PAD src0_sel:WORD_1
	v_pk_fma_f32 v[164:165], v[94:95], v[212:213], v[164:165]
	v_cvt_pk_f16_f32 v31, v30, v31
	v_cvt_pk_f16_f32 v30, v164, v165
	v_pk_fma_f32 v[32:33], v[92:93], v[206:207], v[162:163]
	v_add_co_u32_e32 v162, vcc, s44, v226
	v_cvt_pk_f16_f32 v33, v32, v33
	v_cvt_pk_f16_f32 v32, v166, v167
	v_addc_co_u32_e32 v163, vcc, 0, v227, vcc
	global_store_dwordx4 v[162:163], v[30:33], off
	s_waitcnt vmcnt(15)
; __device__ __forceinline__ u32x2 f32x4_to_h4(f32x4 v) { return __builtin_bit_cast(u32x2, __builtin_convertvector(v, f16x4)); }
; __device__ __forceinline__ f32x4 h4_to_f32x4(u32x2 v) { return __builtin_convertvector(__builtin_bit_cast(f16x4, v), f32x4); }
;     __device__ __forceinline__ void operator()(const f32x4 (&acc)[2][2][4][2], const pg8::Unit& u, int wr, int wc, int fr, int fq) const {
;     ...
;                     for (int bj = 0; bj < 2; ++bj) { const size_t ro = (size_t)(ai * 128 + m * 16) * D + bj * 128; const u32x4 hv = hb[ai][m][bj];
;                         const f32x4 v0 = h4_to_f32x4((u32x2){hv.x, hv.y}) + gvv[bj][0] * acc[ai][bj][m][0], v1 = h4_to_f32x4((u32x2){hv.z, hv.w}) + gvv[bj][1] * acc[ai][bj][m][1];
;                         if constexpr (OUT_F32) { *(f32x4*)((float*)out + oo + ro) = v0; *(f32x4*)((float*)out + oo + ro + 4) = v1; }
;                         else { const u32x2 h0 = f32x4_to_h4(v0), h1 = f32x4_to_h4(v1); *(u32x4*)((_Float16*)out + oo + ro) = (u32x4){h0.x, h0.y, h1.x, h1.y}; } }
	v_cvt_f32_f16_e32 v164, v28
	v_cvt_f32_f16_sdwa v165, v28 dst_sel:DWORD dst_unused:UNUSED_PAD src0_sel:WORD_1
	v_cvt_f32_f16_e32 v30, v27
	v_cvt_f32_f16_sdwa v31, v27 dst_sel:DWORD dst_unused:UNUSED_PAD src0_sel:WORD_1
	v_cvt_f32_f16_e32 v32, v26
	v_cvt_f32_f16_sdwa v33, v26 dst_sel:DWORD dst_unused:UNUSED_PAD src0_sel:WORD_1
	v_pk_fma_f32 v[164:165], v[74:75], v[216:217], v[164:165]
	v_pk_fma_f32 v[26:27], v[84:85], v[218:219], v[30:31]
	v_cvt_f32_f16_e32 v30, v29
	v_cvt_f32_f16_sdwa v31, v29 dst_sel:DWORD dst_unused:UNUSED_PAD src0_sel:WORD_1
	v_pk_fma_f32 v[32:33], v[82:83], v[220:221], v[32:33]
	v_cvt_pk_f16_f32 v27, v26, v27
	v_cvt_pk_f16_f32 v26, v32, v33
	v_pk_fma_f32 v[28:29], v[76:77], v[214:215], v[30:31]
	s_waitcnt vmcnt(14)
	v_cvt_f32_f16_e32 v30, v24
	v_cvt_pk_f16_f32 v29, v28, v29
	v_cvt_pk_f16_f32 v28, v164, v165
	global_store_dwordx4 v[162:163], v[26:29], off offset:256
	v_cvt_f32_f16_sdwa v31, v24 dst_sel:DWORD dst_unused:UNUSED_PAD src0_sel:WORD_1
	v_pk_fma_f32 v[30:31], v[78:79], v[208:209], v[30:31]
	v_cvt_f32_f16_e32 v26, v23
	v_cvt_f32_f16_sdwa v27, v23 dst_sel:DWORD dst_unused:UNUSED_PAD src0_sel:WORD_1
	v_cvt_f32_f16_e32 v28, v22
	v_cvt_f32_f16_sdwa v29, v22 dst_sel:DWORD dst_unused:UNUSED_PAD src0_sel:WORD_1
	v_pk_fma_f32 v[22:23], v[88:89], v[210:211], v[26:27]
	v_cvt_f32_f16_e32 v26, v25
	v_cvt_f32_f16_sdwa v27, v25 dst_sel:DWORD dst_unused:UNUSED_PAD src0_sel:WORD_1
	v_pk_fma_f32 v[28:29], v[86:87], v[212:213], v[28:29]
	v_cvt_pk_f16_f32 v23, v22, v23
	v_cvt_pk_f16_f32 v22, v28, v29
	v_pk_fma_f32 v[24:25], v[80:81], v[206:207], v[26:27]
	v_add_co_u32_e32 v26, vcc, s45, v226
	v_cvt_pk_f16_f32 v25, v24, v25
	v_cvt_pk_f16_f32 v24, v30, v31
	v_addc_co_u32_e32 v27, vcc, 0, v227, vcc
	global_store_dwordx4 v[26:27], v[22:25], off
	s_waitcnt vmcnt(15)
	v_cvt_f32_f16_e32 v28, v20
	v_cvt_f32_f16_sdwa v29, v20 dst_sel:DWORD dst_unused:UNUSED_PAD src0_sel:WORD_1
	v_cvt_f32_f16_e32 v22, v19
	v_cvt_f32_f16_sdwa v23, v19 dst_sel:DWORD dst_unused:UNUSED_PAD src0_sel:WORD_1
	v_cvt_f32_f16_e32 v24, v18
	v_cvt_f32_f16_sdwa v25, v18 dst_sel:DWORD dst_unused:UNUSED_PAD src0_sel:WORD_1
	v_pk_fma_f32 v[28:29], v[58:59], v[216:217], v[28:29]
	v_pk_fma_f32 v[18:19], v[68:69], v[218:219], v[22:23]
	v_cvt_f32_f16_e32 v22, v21
	v_cvt_f32_f16_sdwa v23, v21 dst_sel:DWORD dst_unused:UNUSED_PAD src0_sel:WORD_1
	v_pk_fma_f32 v[24:25], v[66:67], v[220:221], v[24:25]
	v_cvt_pk_f16_f32 v19, v18, v19
	v_cvt_pk_f16_f32 v18, v24, v25
	v_pk_fma_f32 v[20:21], v[60:61], v[214:215], v[22:23]
	s_waitcnt vmcnt(14)
	v_cvt_f32_f16_e32 v22, v16
	v_cvt_pk_f16_f32 v21, v20, v21
	v_cvt_pk_f16_f32 v20, v28, v29
	global_store_dwordx4 v[26:27], v[18:21], off offset:256
	v_cvt_f32_f16_sdwa v23, v16 dst_sel:DWORD dst_unused:UNUSED_PAD src0_sel:WORD_1
	v_pk_fma_f32 v[22:23], v[62:63], v[208:209], v[22:23]
	v_cvt_f32_f16_e32 v18, v15
	v_cvt_f32_f16_sdwa v19, v15 dst_sel:DWORD dst_unused:UNUSED_PAD src0_sel:WORD_1
	v_cvt_f32_f16_e32 v20, v14
	v_cvt_f32_f16_sdwa v21, v14 dst_sel:DWORD dst_unused:UNUSED_PAD src0_sel:WORD_1
	v_pk_fma_f32 v[14:15], v[72:73], v[210:211], v[18:19]
	v_cvt_f32_f16_e32 v18, v17
	v_cvt_f32_f16_sdwa v19, v17 dst_sel:DWORD dst_unused:UNUSED_PAD src0_sel:WORD_1
	v_pk_fma_f32 v[20:21], v[70:71], v[212:213], v[20:21]
	v_cvt_pk_f16_f32 v15, v14, v15
	v_cvt_pk_f16_f32 v14, v20, v21
	v_pk_fma_f32 v[16:17], v[64:65], v[206:207], v[18:19]
	v_add_co_u32_e32 v18, vcc, s46, v226
	v_cvt_pk_f16_f32 v17, v16, v17
	v_cvt_pk_f16_f32 v16, v22, v23
	v_addc_co_u32_e32 v19, vcc, 0, v227, vcc
	global_store_dwordx4 v[18:19], v[14:17], off
	s_waitcnt vmcnt(15)
	v_cvt_f32_f16_e32 v20, v12
	v_cvt_f32_f16_sdwa v21, v12 dst_sel:DWORD dst_unused:UNUSED_PAD src0_sel:WORD_1
	v_cvt_f32_f16_e32 v14, v11
	v_cvt_f32_f16_sdwa v15, v11 dst_sel:DWORD dst_unused:UNUSED_PAD src0_sel:WORD_1
	v_cvt_f32_f16_e32 v16, v10
	v_cvt_f32_f16_sdwa v17, v10 dst_sel:DWORD dst_unused:UNUSED_PAD src0_sel:WORD_1
	v_pk_fma_f32 v[20:21], v[42:43], v[216:217], v[20:21]
	v_pk_fma_f32 v[10:11], v[52:53], v[218:219], v[14:15]
	v_cvt_f32_f16_e32 v14, v13
	v_cvt_f32_f16_sdwa v15, v13 dst_sel:DWORD dst_unused:UNUSED_PAD src0_sel:WORD_1
	v_pk_fma_f32 v[16:17], v[50:51], v[220:221], v[16:17]
	v_cvt_pk_f16_f32 v11, v10, v11
	v_cvt_pk_f16_f32 v10, v16, v17
	v_pk_fma_f32 v[12:13], v[44:45], v[214:215], v[14:15]
	s_waitcnt vmcnt(14)
	v_cvt_f32_f16_e32 v14, v8
	v_cvt_pk_f16_f32 v13, v12, v13
	v_cvt_pk_f16_f32 v12, v20, v21
	global_store_dwordx4 v[18:19], v[10:13], off offset:256
	v_cvt_f32_f16_sdwa v15, v8 dst_sel:DWORD dst_unused:UNUSED_PAD src0_sel:WORD_1
	v_pk_fma_f32 v[14:15], v[46:47], v[208:209], v[14:15]
	v_cvt_f32_f16_e32 v10, v7
	v_cvt_f32_f16_sdwa v11, v7 dst_sel:DWORD dst_unused:UNUSED_PAD src0_sel:WORD_1
	v_cvt_f32_f16_e32 v12, v6
	v_cvt_f32_f16_sdwa v13, v6 dst_sel:DWORD dst_unused:UNUSED_PAD src0_sel:WORD_1
	v_pk_fma_f32 v[6:7], v[56:57], v[210:211], v[10:11]
	v_cvt_f32_f16_e32 v10, v9
	v_cvt_f32_f16_sdwa v11, v9 dst_sel:DWORD dst_unused:UNUSED_PAD src0_sel:WORD_1
	v_pk_fma_f32 v[12:13], v[54:55], v[212:213], v[12:13]
	v_cvt_pk_f16_f32 v7, v6, v7
	v_cvt_pk_f16_f32 v6, v12, v13
	v_pk_fma_f32 v[8:9], v[48:49], v[206:207], v[10:11]
	v_add_co_u32_e32 v10, vcc, s47, v226
	v_cvt_pk_f16_f32 v9, v8, v9
	v_cvt_pk_f16_f32 v8, v14, v15
	v_addc_co_u32_e32 v11, vcc, 0, v227, vcc
	global_store_dwordx4 v[10:11], v[6:9], off
	s_waitcnt vmcnt(15)
	v_cvt_f32_f16_e32 v12, v4
	v_cvt_f32_f16_sdwa v13, v4 dst_sel:DWORD dst_unused:UNUSED_PAD src0_sel:WORD_1
	v_cvt_f32_f16_e32 v6, v3
	v_cvt_f32_f16_sdwa v7, v3 dst_sel:DWORD dst_unused:UNUSED_PAD src0_sel:WORD_1
	v_cvt_f32_f16_e32 v8, v2
	v_cvt_f32_f16_sdwa v9, v2 dst_sel:DWORD dst_unused:UNUSED_PAD src0_sel:WORD_1
	v_pk_fma_f32 v[12:13], v[34:35], v[216:217], v[12:13]
	v_pk_fma_f32 v[2:3], v[40:41], v[218:219], v[6:7]
	v_cvt_f32_f16_e32 v6, v5
	v_cvt_f32_f16_sdwa v7, v5 dst_sel:DWORD dst_unused:UNUSED_PAD src0_sel:WORD_1
	v_pk_fma_f32 v[8:9], v[38:39], v[220:221], v[8:9]
	v_cvt_pk_f16_f32 v3, v2, v3
	v_cvt_pk_f16_f32 v2, v8, v9
	v_pk_fma_f32 v[4:5], v[36:37], v[214:215], v[6:7]
	s_nop 0
	v_cvt_pk_f16_f32 v5, v4, v5
	v_cvt_pk_f16_f32 v4, v12, v13
	global_store_dwordx4 v[10:11], v[2:5], off offset:256
	s_cbranch_execz .LBB0_1313

;     __device__ __forceinline__ void operator()(const f32x4 (&acc)[2][2][4][2], const pg8::Unit& u, int wr, int wc, int fr, int fq) const {
;         const float coef = __builtin_bit_cast(float, __builtin_amdgcn_readfirstlane(__builtin_bit_cast(int, this->coef)));
;         GAS float* const part = (GAS float*)(((unsigned long long)(unsigned)__builtin_amdgcn_readfirstlane((int)((unsigned long long)this->part >> 32)) << 32) | (unsigned)__builtin_amdgcn_readfirstlane((int)(unsigned long long)this->part));
;         const int row0 = u.pm * 256 + wr * 64 + fr, col0 = u.pn * 256 + wc * 32 + 8 * fq;
;         const int r = u.pm < 64 ? (u.pm >> 3) : 8;
;         const float* gv = gate + (size_t)r * DMODW + col0;
;         f32x4 gvv[2][2];
; #pragma unroll
;         for (int bj = 0; bj < 2; ++bj)
; #pragma unroll
;             for (int n = 0; n < 2; ++n) gvv[bj][n] = *(const f32x4*)(gv + bj * 128 + 4 * n) * coef;
;         if (u.kind >= 2) {
;             GAS float* op = part + (size_t)(u.kind - 2) * (PART_STRIDE / 4) + (size_t)(row0 - M_LAT) * D + col0;
; #pragma unroll
;             for (int ai = 0; ai < 2; ++ai)
; #pragma unroll
;                 for (int m = 0; m < 4; ++m) { const size_t ro = (size_t)(ai * 128 + m * 16) * D;
; #pragma unroll
;                     for (int bj = 0; bj < 2; ++bj)
; #pragma unroll
;                         for (int n = 0; n < 2; ++n) *(GAS f32x4*)(op + ro + bj * 128 + 4 * n) = gvv[bj][n] * acc[ai][bj][m][n]; }
;             return;
;         }
;         const size_t eo = (u.pm < 64 ? (size_t)row0 : (size_t)(row0 - M_LAT)) * D + col0;
;         const void* bsel = u.pm < 64 ? base_lat : base_ctx;
;         const size_t oo = (size_t)row0 * D + col0;
;         if constexpr (!BASE_F32) {
;             u32x4 hb[2][4][2];
; #pragma unroll
;             for (int ai = 0; ai < 2; ++ai)
; #pragma unroll
;                 for (int m = 0; m < 4; ++m)
; #pragma unroll
;                     for (int bj = 0; bj < 2; ++bj) hb[ai][m][bj] = *(const u32x4*)((const _Float16*)bsel + eo + (size_t)(ai * 128 + m * 16) * D + bj * 128);
; #pragma unroll
;             for (int ai = 0; ai < 2; ++ai)
; #pragma unroll
;                 for (int m = 0; m < 4; ++m)
; #pragma unroll
;                     for (int bj = 0; bj < 2; ++bj) { const size_t ro = (size_t)(ai * 128 + m * 16) * D + bj * 128; const u32x4 hv = hb[ai][m][bj];
.LBB0_1700:
	s_lshl_b64 s[20:21], s[20:21], 2
	v_lshl_or_b32 v224, s69, 8, v232
	s_add_u32 s20, s34, s20
	s_addc_u32 s21, s35, s21
	v_ashrrev_i32_e32 v225, 31, v224
	v_lshl_add_u64 v[10:11], v[224:225], 2, s[20:21]
	global_load_dwordx4 v[2:5], v[10:11], off offset:16
	global_load_dwordx4 v[6:9], v[10:11], off
	v_lshl_add_u32 v222, s70, 8, v230
	s_mov_b64 s[20:21], -1
	s_cmp_lt_i32 s49, 2
	v_ashrrev_i32_e32 v223, 31, v222
	s_waitcnt vmcnt(0)
	v_pk_mul_f32 v[206:207], v[4:5], s[14:15] op_sel_hi:[1,0]
	v_pk_mul_f32 v[210:211], v[8:9], s[14:15] op_sel_hi:[1,0]
	v_pk_mul_f32 v[212:213], v[6:7], s[14:15] op_sel_hi:[1,0]
	v_pk_mul_f32 v[208:209], v[2:3], s[14:15] op_sel_hi:[1,0]
	global_load_dwordx4 v[2:5], v[10:11], off offset:528
	global_load_dwordx4 v[6:9], v[10:11], off offset:512
	s_waitcnt vmcnt(1)
	v_pk_mul_f32 v[214:215], v[4:5], s[14:15] op_sel_hi:[1,0]
	s_waitcnt vmcnt(0)
	v_pk_mul_f32 v[218:219], v[8:9], s[14:15] op_sel_hi:[1,0]
	v_pk_mul_f32 v[220:221], v[6:7], s[14:15] op_sel_hi:[1,0]
	v_pk_mul_f32 v[216:217], v[2:3], s[14:15] op_sel_hi:[1,0]
	s_cbranch_scc0 .LBB0_1703
	v_add_u32_e32 v2, 0xffffc000, v222
	v_cndmask_b32_e32 v2, v2, v222, vcc
	v_readlane_b32 s22, v253, 52
	v_ashrrev_i32_e32 v3, 31, v2
	s_and_b64 s[20:21], vcc, exec
	v_readlane_b32 s23, v253, 53
	s_cselect_b32 s21, s23, s7
	s_cselect_b32 s20, s22, s6
	v_lshlrev_b64 v[2:3], 12, v[2:3]
	v_lshl_add_u64 v[2:3], s[20:21], 0, v[2:3]
	v_lshlrev_b64 v[226:227], 1, v[224:225]
	v_lshl_add_u64 v[2:3], v[2:3], 0, v[226:227]
	global_load_dwordx4 v[236:239], v[2:3], off nt
	global_load_dwordx4 v[186:189], v[2:3], off offset:256 nt
	v_add_co_u32_e32 v4, vcc, s33, v2
	v_lshlrev_b64 v[240:241], 12, v[222:223]
	s_nop 0
	v_addc_co_u32_e32 v5, vcc, 0, v3, vcc
	global_load_dwordx4 v[182:185], v[4:5], off nt
	global_load_dwordx4 v[178:181], v[4:5], off offset:256 nt
	v_add_co_u32_e32 v4, vcc, s42, v2
	v_lshl_add_u64 v[240:241], s[22:23], 0, v[240:241]
	s_nop 0
	v_addc_co_u32_e32 v5, vcc, 0, v3, vcc
	global_load_dwordx4 v[174:177], v[4:5], off nt
	global_load_dwordx4 v[170:173], v[4:5], off offset:256 nt
	v_add_co_u32_e32 v4, vcc, s43, v2
	v_lshl_add_u64 v[226:227], v[240:241], 0, v[226:227]
	s_nop 0
	v_addc_co_u32_e32 v5, vcc, 0, v3, vcc
	global_load_dwordx4 v[166:169], v[4:5], off nt
	global_load_dwordx4 v[162:165], v[4:5], off offset:256 nt
	v_add_co_u32_e32 v4, vcc, s44, v2
	s_nop 1
	v_addc_co_u32_e32 v5, vcc, 0, v3, vcc
	global_load_dwordx4 v[30:33], v[4:5], off nt
	global_load_dwordx4 v[26:29], v[4:5], off offset:256 nt
	v_add_co_u32_e32 v4, vcc, s45, v2
	s_waitcnt vmcnt(9)
	v_cvt_f32_f16_e32 v242, v237
	v_cvt_f32_f16_sdwa v243, v237 dst_sel:DWORD dst_unused:UNUSED_PAD src0_sel:WORD_1
	v_cvt_f32_f16_e32 v244, v236
	v_cvt_f32_f16_sdwa v245, v236 dst_sel:DWORD dst_unused:UNUSED_PAD src0_sel:WORD_1
	v_cvt_f32_f16_e32 v246, v238
	v_pk_fma_f32 v[236:237], v[160:161], v[210:211], v[242:243]
	v_cvt_f32_f16_e32 v242, v239
	v_cvt_f32_f16_sdwa v243, v239 dst_sel:DWORD dst_unused:UNUSED_PAD src0_sel:WORD_1
	v_cvt_f32_f16_sdwa v247, v238 dst_sel:DWORD dst_unused:UNUSED_PAD src0_sel:WORD_1
	v_addc_co_u32_e32 v5, vcc, 0, v3, vcc
	global_load_dwordx4 v[22:25], v[4:5], off nt
	global_load_dwordx4 v[18:21], v[4:5], off offset:256 nt
	v_add_co_u32_e32 v4, vcc, s46, v2
	v_pk_fma_f32 v[244:245], v[158:159], v[212:213], v[244:245]
	s_nop 0
	v_addc_co_u32_e32 v5, vcc, 0, v3, vcc
	v_add_co_u32_e32 v2, vcc, s47, v2
	v_pk_fma_f32 v[246:247], v[154:155], v[208:209], v[246:247]
	v_pk_fma_f32 v[238:239], v[156:157], v[206:207], v[242:243]
	v_addc_co_u32_e32 v3, vcc, 0, v3, vcc
	v_cvt_pk_f16_f32 v237, v236, v237
	v_cvt_pk_f16_f32 v236, v244, v245
	v_cvt_pk_f16_f32 v239, v238, v239
	v_cvt_pk_f16_f32 v238, v246, v247
	global_load_dwordx4 v[14:17], v[4:5], off nt
	global_load_dwordx4 v[10:13], v[4:5], off offset:256 nt
	global_load_dwordx4 v[6:9], v[2:3], off nt
	s_nop 0
	global_load_dwordx4 v[2:5], v[2:3], off offset:256 nt
	s_waitcnt vmcnt(14)
	v_cvt_f32_f16_e32 v240, v188
	global_store_dwordx4 v[226:227], v[236:239], off
	v_cvt_f32_f16_sdwa v241, v188 dst_sel:DWORD dst_unused:UNUSED_PAD src0_sel:WORD_1
	v_pk_fma_f32 v[240:241], v[138:139], v[216:217], v[240:241]
	v_cvt_f32_f16_e32 v236, v187
	v_cvt_f32_f16_sdwa v237, v187 dst_sel:DWORD dst_unused:UNUSED_PAD src0_sel:WORD_1
	v_cvt_f32_f16_e32 v238, v186
	v_cvt_f32_f16_sdwa v239, v186 dst_sel:DWORD dst_unused:UNUSED_PAD src0_sel:WORD_1
	v_pk_fma_f32 v[186:187], v[148:149], v[218:219], v[236:237]
	v_cvt_f32_f16_e32 v236, v189
	v_cvt_f32_f16_sdwa v237, v189 dst_sel:DWORD dst_unused:UNUSED_PAD src0_sel:WORD_1
	v_pk_fma_f32 v[238:239], v[146:147], v[220:221], v[238:239]
	v_cvt_pk_f16_f32 v187, v186, v187
	v_cvt_pk_f16_f32 v186, v238, v239
	v_pk_fma_f32 v[188:189], v[140:141], v[214:215], v[236:237]
	s_waitcnt vmcnt(14)
	v_cvt_f32_f16_e32 v236, v184
	v_cvt_pk_f16_f32 v189, v188, v189
	v_cvt_pk_f16_f32 v188, v240, v241
	global_store_dwordx4 v[226:227], v[186:189], off offset:256
	v_cvt_f32_f16_sdwa v237, v184 dst_sel:DWORD dst_unused:UNUSED_PAD src0_sel:WORD_1
	v_pk_fma_f32 v[236:237], v[142:143], v[208:209], v[236:237]
	v_cvt_f32_f16_e32 v186, v183
	v_cvt_f32_f16_sdwa v187, v183 dst_sel:DWORD dst_unused:UNUSED_PAD src0_sel:WORD_1
	v_cvt_f32_f16_e32 v188, v182
	v_cvt_f32_f16_sdwa v189, v182 dst_sel:DWORD dst_unused:UNUSED_PAD src0_sel:WORD_1
	v_pk_fma_f32 v[182:183], v[152:153], v[210:211], v[186:187]
	v_cvt_f32_f16_e32 v186, v185
	v_cvt_f32_f16_sdwa v187, v185 dst_sel:DWORD dst_unused:UNUSED_PAD src0_sel:WORD_1
	v_pk_fma_f32 v[188:189], v[150:151], v[212:213], v[188:189]
	v_cvt_pk_f16_f32 v183, v182, v183
	v_cvt_pk_f16_f32 v182, v188, v189
	v_pk_fma_f32 v[184:185], v[144:145], v[206:207], v[186:187]
	v_add_co_u32_e32 v186, vcc, s33, v226
	v_cvt_pk_f16_f32 v185, v184, v185
	v_cvt_pk_f16_f32 v184, v236, v237
	v_addc_co_u32_e32 v187, vcc, 0, v227, vcc
	global_store_dwordx4 v[186:187], v[182:185], off
	s_waitcnt vmcnt(15)
; __device__ __forceinline__ u32x2 f32x4_to_h4(f32x4 v) { return __builtin_bit_cast(u32x2, __builtin_convertvector(v, f16x4)); }
; __device__ __forceinline__ f32x4 h4_to_f32x4(u32x2 v) { return __builtin_convertvector(__builtin_bit_cast(f16x4, v), f32x4); }
;     __device__ __forceinline__ void operator()(const f32x4 (&acc)[2][2][4][2], const pg8::Unit& u, int wr, int wc, int fr, int fq) const {
;     ...
;                     for (int bj = 0; bj < 2; ++bj) { const size_t ro = (size_t)(ai * 128 + m * 16) * D + bj * 128; const u32x4 hv = hb[ai][m][bj];
;                         const f32x4 v0 = h4_to_f32x4((u32x2){hv.x, hv.y}) + gvv[bj][0] * acc[ai][bj][m][0], v1 = h4_to_f32x4((u32x2){hv.z, hv.w}) + gvv[bj][1] * acc[ai][bj][m][1];
;                         if constexpr (OUT_F32) { *(f32x4*)((float*)out + oo + ro) = v0; *(f32x4*)((float*)out + oo + ro + 4) = v1; }
;                         else { const u32x2 h0 = f32x4_to_h4(v0), h1 = f32x4_to_h4(v1); *(u32x4*)((_Float16*)out + oo + ro) = (u32x4){h0.x, h0.y, h1.x, h1.y}; } }
	v_cvt_f32_f16_e32 v188, v180
	v_cvt_f32_f16_sdwa v189, v180 dst_sel:DWORD dst_unused:UNUSED_PAD src0_sel:WORD_1
	v_cvt_f32_f16_e32 v182, v179
	v_cvt_f32_f16_sdwa v183, v179 dst_sel:DWORD dst_unused:UNUSED_PAD src0_sel:WORD_1
	v_cvt_f32_f16_e32 v184, v178
	v_cvt_f32_f16_sdwa v185, v178 dst_sel:DWORD dst_unused:UNUSED_PAD src0_sel:WORD_1
	v_pk_fma_f32 v[188:189], v[122:123], v[216:217], v[188:189]
	v_pk_fma_f32 v[178:179], v[132:133], v[218:219], v[182:183]
	v_cvt_f32_f16_e32 v182, v181
	v_cvt_f32_f16_sdwa v183, v181 dst_sel:DWORD dst_unused:UNUSED_PAD src0_sel:WORD_1
	v_pk_fma_f32 v[184:185], v[130:131], v[220:221], v[184:185]
	v_cvt_pk_f16_f32 v179, v178, v179
	v_cvt_pk_f16_f32 v178, v184, v185
	v_pk_fma_f32 v[180:181], v[124:125], v[214:215], v[182:183]
	s_waitcnt vmcnt(14)
	v_cvt_f32_f16_e32 v182, v176
	v_cvt_pk_f16_f32 v181, v180, v181
	v_cvt_pk_f16_f32 v180, v188, v189
	global_store_dwordx4 v[186:187], v[178:181], off offset:256
	v_cvt_f32_f16_sdwa v183, v176 dst_sel:DWORD dst_unused:UNUSED_PAD src0_sel:WORD_1
	v_pk_fma_f32 v[182:183], v[126:127], v[208:209], v[182:183]
	v_cvt_f32_f16_e32 v178, v175
	v_cvt_f32_f16_sdwa v179, v175 dst_sel:DWORD dst_unused:UNUSED_PAD src0_sel:WORD_1
	v_cvt_f32_f16_e32 v180, v174
	v_cvt_f32_f16_sdwa v181, v174 dst_sel:DWORD dst_unused:UNUSED_PAD src0_sel:WORD_1
	v_pk_fma_f32 v[174:175], v[136:137], v[210:211], v[178:179]
	v_cvt_f32_f16_e32 v178, v177
	v_cvt_f32_f16_sdwa v179, v177 dst_sel:DWORD dst_unused:UNUSED_PAD src0_sel:WORD_1
	v_pk_fma_f32 v[180:181], v[134:135], v[212:213], v[180:181]
	v_cvt_pk_f16_f32 v175, v174, v175
	v_cvt_pk_f16_f32 v174, v180, v181
	v_pk_fma_f32 v[176:177], v[128:129], v[206:207], v[178:179]
	v_add_co_u32_e32 v178, vcc, s42, v226
	v_cvt_pk_f16_f32 v177, v176, v177
	v_cvt_pk_f16_f32 v176, v182, v183
	v_addc_co_u32_e32 v179, vcc, 0, v227, vcc
	global_store_dwordx4 v[178:179], v[174:177], off
	s_waitcnt vmcnt(15)
	v_cvt_f32_f16_e32 v180, v172
	v_cvt_f32_f16_sdwa v181, v172 dst_sel:DWORD dst_unused:UNUSED_PAD src0_sel:WORD_1
	v_cvt_f32_f16_e32 v174, v171
	v_cvt_f32_f16_sdwa v175, v171 dst_sel:DWORD dst_unused:UNUSED_PAD src0_sel:WORD_1
	v_cvt_f32_f16_e32 v176, v170
	v_cvt_f32_f16_sdwa v177, v170 dst_sel:DWORD dst_unused:UNUSED_PAD src0_sel:WORD_1
	v_pk_fma_f32 v[180:181], v[106:107], v[216:217], v[180:181]
	v_pk_fma_f32 v[170:171], v[116:117], v[218:219], v[174:175]
	v_cvt_f32_f16_e32 v174, v173
	v_cvt_f32_f16_sdwa v175, v173 dst_sel:DWORD dst_unused:UNUSED_PAD src0_sel:WORD_1
	v_pk_fma_f32 v[176:177], v[114:115], v[220:221], v[176:177]
	v_cvt_pk_f16_f32 v171, v170, v171
	v_cvt_pk_f16_f32 v170, v176, v177
	v_pk_fma_f32 v[172:173], v[108:109], v[214:215], v[174:175]
	s_waitcnt vmcnt(14)
	v_cvt_f32_f16_e32 v174, v168
	v_cvt_pk_f16_f32 v173, v172, v173
	v_cvt_pk_f16_f32 v172, v180, v181
	global_store_dwordx4 v[178:179], v[170:173], off offset:256
	v_cvt_f32_f16_sdwa v175, v168 dst_sel:DWORD dst_unused:UNUSED_PAD src0_sel:WORD_1
	v_pk_fma_f32 v[174:175], v[110:111], v[208:209], v[174:175]
	v_cvt_f32_f16_e32 v170, v167
	v_cvt_f32_f16_sdwa v171, v167 dst_sel:DWORD dst_unused:UNUSED_PAD src0_sel:WORD_1
	v_cvt_f32_f16_e32 v172, v166
	v_cvt_f32_f16_sdwa v173, v166 dst_sel:DWORD dst_unused:UNUSED_PAD src0_sel:WORD_1
	v_pk_fma_f32 v[166:167], v[120:121], v[210:211], v[170:171]
	v_cvt_f32_f16_e32 v170, v169
	v_cvt_f32_f16_sdwa v171, v169 dst_sel:DWORD dst_unused:UNUSED_PAD src0_sel:WORD_1
	v_pk_fma_f32 v[172:173], v[118:119], v[212:213], v[172:173]
	v_cvt_pk_f16_f32 v167, v166, v167
	v_cvt_pk_f16_f32 v166, v172, v173
	v_pk_fma_f32 v[168:169], v[112:113], v[206:207], v[170:171]
	v_add_co_u32_e32 v170, vcc, s43, v226
	v_cvt_pk_f16_f32 v169, v168, v169
	v_cvt_pk_f16_f32 v168, v174, v175
	v_addc_co_u32_e32 v171, vcc, 0, v227, vcc
	global_store_dwordx4 v[170:171], v[166:169], off
	s_waitcnt vmcnt(15)
	v_cvt_f32_f16_e32 v172, v164
	v_cvt_f32_f16_sdwa v173, v164 dst_sel:DWORD dst_unused:UNUSED_PAD src0_sel:WORD_1
	v_cvt_f32_f16_e32 v166, v163
	v_cvt_f32_f16_sdwa v167, v163 dst_sel:DWORD dst_unused:UNUSED_PAD src0_sel:WORD_1
	v_cvt_f32_f16_e32 v168, v162
	v_cvt_f32_f16_sdwa v169, v162 dst_sel:DWORD dst_unused:UNUSED_PAD src0_sel:WORD_1
	v_pk_fma_f32 v[172:173], v[98:99], v[216:217], v[172:173]
	v_pk_fma_f32 v[162:163], v[104:105], v[218:219], v[166:167]
	v_cvt_f32_f16_e32 v166, v165
	v_cvt_f32_f16_sdwa v167, v165 dst_sel:DWORD dst_unused:UNUSED_PAD src0_sel:WORD_1
	v_pk_fma_f32 v[168:169], v[102:103], v[220:221], v[168:169]
	v_cvt_pk_f16_f32 v163, v162, v163
	v_cvt_pk_f16_f32 v162, v168, v169
	v_pk_fma_f32 v[164:165], v[100:101], v[214:215], v[166:167]
	s_waitcnt vmcnt(14)
	v_cvt_f32_f16_e32 v166, v32
	v_cvt_pk_f16_f32 v165, v164, v165
	v_cvt_pk_f16_f32 v164, v172, v173
	global_store_dwordx4 v[170:171], v[162:165], off offset:256
	v_cvt_f32_f16_sdwa v167, v32 dst_sel:DWORD dst_unused:UNUSED_PAD src0_sel:WORD_1
	v_pk_fma_f32 v[166:167], v[90:91], v[208:209], v[166:167]
	v_cvt_f32_f16_e32 v162, v31
	v_cvt_f32_f16_sdwa v163, v31 dst_sel:DWORD dst_unused:UNUSED_PAD src0_sel:WORD_1
	v_cvt_f32_f16_e32 v164, v30
	v_cvt_f32_f16_sdwa v165, v30 dst_sel:DWORD dst_unused:UNUSED_PAD src0_sel:WORD_1
	v_pk_fma_f32 v[30:31], v[96:97], v[210:211], v[162:163]
	v_cvt_f32_f16_e32 v162, v33
	v_cvt_f32_f16_sdwa v163, v33 dst_sel:DWORD dst_unused:UNUSED_PAD src0_sel:WORD_1
	v_pk_fma_f32 v[164:165], v[94:95], v[212:213], v[164:165]
	v_cvt_pk_f16_f32 v31, v30, v31
	v_cvt_pk_f16_f32 v30, v164, v165
	v_pk_fma_f32 v[32:33], v[92:93], v[206:207], v[162:163]
	v_add_co_u32_e32 v162, vcc, s44, v226
	v_cvt_pk_f16_f32 v33, v32, v33
	v_cvt_pk_f16_f32 v32, v166, v167
	v_addc_co_u32_e32 v163, vcc, 0, v227, vcc
	global_store_dwordx4 v[162:163], v[30:33], off
	s_waitcnt vmcnt(15)
; __device__ __forceinline__ u32x2 f32x4_to_h4(f32x4 v) { return __builtin_bit_cast(u32x2, __builtin_convertvector(v, f16x4)); }
; __device__ __forceinline__ f32x4 h4_to_f32x4(u32x2 v) { return __builtin_convertvector(__builtin_bit_cast(f16x4, v), f32x4); }
;     __device__ __forceinline__ void operator()(const f32x4 (&acc)[2][2][4][2], const pg8::Unit& u, int wr, int wc, int fr, int fq) const {
;     ...
;                     for (int bj = 0; bj < 2; ++bj) { const size_t ro = (size_t)(ai * 128 + m * 16) * D + bj * 128; const u32x4 hv = hb[ai][m][bj];
;                         const f32x4 v0 = h4_to_f32x4((u32x2){hv.x, hv.y}) + gvv[bj][0] * acc[ai][bj][m][0], v1 = h4_to_f32x4((u32x2){hv.z, hv.w}) + gvv[bj][1] * acc[ai][bj][m][1];
;                         if constexpr (OUT_F32) { *(f32x4*)((float*)out + oo + ro) = v0; *(f32x4*)((float*)out + oo + ro + 4) = v1; }
;                         else { const u32x2 h0 = f32x4_to_h4(v0), h1 = f32x4_to_h4(v1); *(u32x4*)((_Float16*)out + oo + ro) = (u32x4){h0.x, h0.y, h1.x, h1.y}; } }
	v_cvt_f32_f16_e32 v164, v28
	v_cvt_f32_f16_sdwa v165, v28 dst_sel:DWORD dst_unused:UNUSED_PAD src0_sel:WORD_1
	v_cvt_f32_f16_e32 v30, v27
	v_cvt_f32_f16_sdwa v31, v27 dst_sel:DWORD dst_unused:UNUSED_PAD src0_sel:WORD_1
	v_cvt_f32_f16_e32 v32, v26
	v_cvt_f32_f16_sdwa v33, v26 dst_sel:DWORD dst_unused:UNUSED_PAD src0_sel:WORD_1
	v_pk_fma_f32 v[164:165], v[74:75], v[216:217], v[164:165]
	v_pk_fma_f32 v[26:27], v[84:85], v[218:219], v[30:31]
	v_cvt_f32_f16_e32 v30, v29
	v_cvt_f32_f16_sdwa v31, v29 dst_sel:DWORD dst_unused:UNUSED_PAD src0_sel:WORD_1
	v_pk_fma_f32 v[32:33], v[82:83], v[220:221], v[32:33]
	v_cvt_pk_f16_f32 v27, v26, v27
	v_cvt_pk_f16_f32 v26, v32, v33
	v_pk_fma_f32 v[28:29], v[76:77], v[214:215], v[30:31]
	s_waitcnt vmcnt(14)
	v_cvt_f32_f16_e32 v30, v24
	v_cvt_pk_f16_f32 v29, v28, v29
	v_cvt_pk_f16_f32 v28, v164, v165
	global_store_dwordx4 v[162:163], v[26:29], off offset:256
	v_cvt_f32_f16_sdwa v31, v24 dst_sel:DWORD dst_unused:UNUSED_PAD src0_sel:WORD_1
	v_pk_fma_f32 v[30:31], v[78:79], v[208:209], v[30:31]
	v_cvt_f32_f16_e32 v26, v23
	v_cvt_f32_f16_sdwa v27, v23 dst_sel:DWORD dst_unused:UNUSED_PAD src0_sel:WORD_1
	v_cvt_f32_f16_e32 v28, v22
	v_cvt_f32_f16_sdwa v29, v22 dst_sel:DWORD dst_unused:UNUSED_PAD src0_sel:WORD_1
	v_pk_fma_f32 v[22:23], v[88:89], v[210:211], v[26:27]
	v_cvt_f32_f16_e32 v26, v25
	v_cvt_f32_f16_sdwa v27, v25 dst_sel:DWORD dst_unused:UNUSED_PAD src0_sel:WORD_1
	v_pk_fma_f32 v[28:29], v[86:87], v[212:213], v[28:29]
	v_cvt_pk_f16_f32 v23, v22, v23
	v_cvt_pk_f16_f32 v22, v28, v29
	v_pk_fma_f32 v[24:25], v[80:81], v[206:207], v[26:27]
	v_add_co_u32_e32 v26, vcc, s45, v226
	v_cvt_pk_f16_f32 v25, v24, v25
	v_cvt_pk_f16_f32 v24, v30, v31
	v_addc_co_u32_e32 v27, vcc, 0, v227, vcc
	global_store_dwordx4 v[26:27], v[22:25], off
	s_waitcnt vmcnt(15)
	v_cvt_f32_f16_e32 v28, v20
	v_cvt_f32_f16_sdwa v29, v20 dst_sel:DWORD dst_unused:UNUSED_PAD src0_sel:WORD_1
	v_cvt_f32_f16_e32 v22, v19
	v_cvt_f32_f16_sdwa v23, v19 dst_sel:DWORD dst_unused:UNUSED_PAD src0_sel:WORD_1
	v_cvt_f32_f16_e32 v24, v18
	v_cvt_f32_f16_sdwa v25, v18 dst_sel:DWORD dst_unused:UNUSED_PAD src0_sel:WORD_1
	v_pk_fma_f32 v[28:29], v[58:59], v[216:217], v[28:29]
	v_pk_fma_f32 v[18:19], v[68:69], v[218:219], v[22:23]
	v_cvt_f32_f16_e32 v22, v21
	v_cvt_f32_f16_sdwa v23, v21 dst_sel:DWORD dst_unused:UNUSED_PAD src0_sel:WORD_1
	v_pk_fma_f32 v[24:25], v[66:67], v[220:221], v[24:25]
	v_cvt_pk_f16_f32 v19, v18, v19
	v_cvt_pk_f16_f32 v18, v24, v25
	v_pk_fma_f32 v[20:21], v[60:61], v[214:215], v[22:23]
	s_waitcnt vmcnt(14)
	v_cvt_f32_f16_e32 v22, v16
	v_cvt_pk_f16_f32 v21, v20, v21
	v_cvt_pk_f16_f32 v20, v28, v29
	global_store_dwordx4 v[26:27], v[18:21], off offset:256
	v_cvt_f32_f16_sdwa v23, v16 dst_sel:DWORD dst_unused:UNUSED_PAD src0_sel:WORD_1
	v_pk_fma_f32 v[22:23], v[62:63], v[208:209], v[22:23]
	v_cvt_f32_f16_e32 v18, v15
	v_cvt_f32_f16_sdwa v19, v15 dst_sel:DWORD dst_unused:UNUSED_PAD src0_sel:WORD_1
	v_cvt_f32_f16_e32 v20, v14
	v_cvt_f32_f16_sdwa v21, v14 dst_sel:DWORD dst_unused:UNUSED_PAD src0_sel:WORD_1
	v_pk_fma_f32 v[14:15], v[72:73], v[210:211], v[18:19]
	v_cvt_f32_f16_e32 v18, v17
	v_cvt_f32_f16_sdwa v19, v17 dst_sel:DWORD dst_unused:UNUSED_PAD src0_sel:WORD_1
	v_pk_fma_f32 v[20:21], v[70:71], v[212:213], v[20:21]
	v_cvt_pk_f16_f32 v15, v14, v15
	v_cvt_pk_f16_f32 v14, v20, v21
	v_pk_fma_f32 v[16:17], v[64:65], v[206:207], v[18:19]
	v_add_co_u32_e32 v18, vcc, s46, v226
	v_cvt_pk_f16_f32 v17, v16, v17
	v_cvt_pk_f16_f32 v16, v22, v23
	v_addc_co_u32_e32 v19, vcc, 0, v227, vcc
	global_store_dwordx4 v[18:19], v[14:17], off
	s_waitcnt vmcnt(15)
	v_cvt_f32_f16_e32 v20, v12
	v_cvt_f32_f16_sdwa v21, v12 dst_sel:DWORD dst_unused:UNUSED_PAD src0_sel:WORD_1
	v_cvt_f32_f16_e32 v14, v11
	v_cvt_f32_f16_sdwa v15, v11 dst_sel:DWORD dst_unused:UNUSED_PAD src0_sel:WORD_1
	v_cvt_f32_f16_e32 v16, v10
	v_cvt_f32_f16_sdwa v17, v10 dst_sel:DWORD dst_unused:UNUSED_PAD src0_sel:WORD_1
	v_pk_fma_f32 v[20:21], v[42:43], v[216:217], v[20:21]
	v_pk_fma_f32 v[10:11], v[52:53], v[218:219], v[14:15]
	v_cvt_f32_f16_e32 v14, v13
	v_cvt_f32_f16_sdwa v15, v13 dst_sel:DWORD dst_unused:UNUSED_PAD src0_sel:WORD_1
	v_pk_fma_f32 v[16:17], v[50:51], v[220:221], v[16:17]
	v_cvt_pk_f16_f32 v11, v10, v11
	v_cvt_pk_f16_f32 v10, v16, v17
	v_pk_fma_f32 v[12:13], v[44:45], v[214:215], v[14:15]
	s_waitcnt vmcnt(14)
	v_cvt_f32_f16_e32 v14, v8
	v_cvt_pk_f16_f32 v13, v12, v13
	v_cvt_pk_f16_f32 v12, v20, v21
	global_store_dwordx4 v[18:19], v[10:13], off offset:256
	v_cvt_f32_f16_sdwa v15, v8 dst_sel:DWORD dst_unused:UNUSED_PAD src0_sel:WORD_1
	v_pk_fma_f32 v[14:15], v[46:47], v[208:209], v[14:15]
	v_cvt_f32_f16_e32 v10, v7
	v_cvt_f32_f16_sdwa v11, v7 dst_sel:DWORD dst_unused:UNUSED_PAD src0_sel:WORD_1
	v_cvt_f32_f16_e32 v12, v6
	v_cvt_f32_f16_sdwa v13, v6 dst_sel:DWORD dst_unused:UNUSED_PAD src0_sel:WORD_1
	v_pk_fma_f32 v[6:7], v[56:57], v[210:211], v[10:11]
	v_cvt_f32_f16_e32 v10, v9
	v_cvt_f32_f16_sdwa v11, v9 dst_sel:DWORD dst_unused:UNUSED_PAD src0_sel:WORD_1
	v_pk_fma_f32 v[12:13], v[54:55], v[212:213], v[12:13]
	v_cvt_pk_f16_f32 v7, v6, v7
	v_cvt_pk_f16_f32 v6, v12, v13
	v_pk_fma_f32 v[8:9], v[48:49], v[206:207], v[10:11]
	v_add_co_u32_e32 v10, vcc, s47, v226
	v_cvt_pk_f16_f32 v9, v8, v9
	v_cvt_pk_f16_f32 v8, v14, v15
	v_addc_co_u32_e32 v11, vcc, 0, v227, vcc
	global_store_dwordx4 v[10:11], v[6:9], off
	s_waitcnt vmcnt(15)
	v_cvt_f32_f16_e32 v12, v4
	v_cvt_f32_f16_sdwa v13, v4 dst_sel:DWORD dst_unused:UNUSED_PAD src0_sel:WORD_1
	v_cvt_f32_f16_e32 v6, v3
	v_cvt_f32_f16_sdwa v7, v3 dst_sel:DWORD dst_unused:UNUSED_PAD src0_sel:WORD_1
	v_cvt_f32_f16_e32 v8, v2
	v_cvt_f32_f16_sdwa v9, v2 dst_sel:DWORD dst_unused:UNUSED_PAD src0_sel:WORD_1
	v_pk_fma_f32 v[12:13], v[34:35], v[216:217], v[12:13]
	v_pk_fma_f32 v[2:3], v[40:41], v[218:219], v[6:7]
	v_cvt_f32_f16_e32 v6, v5
	v_cvt_f32_f16_sdwa v7, v5 dst_sel:DWORD dst_unused:UNUSED_PAD src0_sel:WORD_1
	v_pk_fma_f32 v[8:9], v[38:39], v[220:221], v[8:9]
	v_cvt_pk_f16_f32 v3, v2, v3
	v_cvt_pk_f16_f32 v2, v8, v9
	v_pk_fma_f32 v[4:5], v[36:37], v[214:215], v[6:7]
	s_nop 0
	v_cvt_pk_f16_f32 v5, v4, v5
	v_cvt_pk_f16_f32 v4, v12, v13
	global_store_dwordx4 v[10:11], v[2:5], off offset:256
	s_cbranch_execz .LBB0_1704

; #define LAS __attribute__((address_space(3)))
; __device__ __forceinline__ float fast_sigmoid(float x) { return __builtin_amdgcn_rcpf(1.0f + __builtin_amdgcn_exp2f(-1.44269504089f * x)); }
; __device__ __forceinline__ void lru_item(const Params& p, LAS unsigned char* lds, int item, int tid, int lane, int wave) {
;     ...
;             for (int q = 0; q < 4; ++q) {
;                 const int tb = tb0 + q;
;                 const bf16x8 a0 = *(const LAS bf16x8*)(xcb + (16 * tb + l15) * 72 + 8 * g), a1 = *(const LAS bf16x8*)(xcb + (16 * tb + l15) * 72 + 8 * g + 32);
;                 f32x4 gr_ = (f32x4){0.f, 0.f, 0.f, 0.f}, gi_ = (f32x4){0.f, 0.f, 0.f, 0.f};
;                 gr_ = __builtin_amdgcn_mfma_f32_16x16x32_bf16(a0, Bg[0][0], gr_, 0, 0, 0); gr_ = __builtin_amdgcn_mfma_f32_16x16x32_bf16(a1, Bg[0][1], gr_, 0, 0, 0);
;                 gi_ = __builtin_amdgcn_mfma_f32_16x16x32_bf16(a0, Bg[1][0], gi_, 0, 0, 0); gi_ = __builtin_amdgcn_mfma_f32_16x16x32_bf16(a1, Bg[1][1], gi_, 0, 0, 0);
; #pragma unroll
;                 for (int e = 0; e < 4; ++e) {
;                     const int tl = 16 * tb + 4 * g + e;
;                     const float rg = fast_sigmoid(gr_[e] + br), ig = fast_sigmoid(gi_[e] + bi);
;                     const float la2 = sp8 * rg, a = __builtin_amdgcn_exp2f(la2);
;                     const float em = __builtin_fmaf(-a, a, 1.0f);
;                     As[tl * 33 + jl] = a; Us[tl * 33 + jl] = __builtin_amdgcn_sqrtf(em) * ig * xcf[tl * 33 + jl];
;                 }
;             }
;             lds_barrier();
;             float av[16], uv[16];
;             {
;                 float A = 1.f, H = 0.f;
;                 const LAS float* ap_ = As + (dir ? (LCH - 1 - 16 * sg) : 16 * sg) * 33 + sc; const LAS float* up_ = Us + (dir ? (LCH - 1 - 16 * sg) : 16 * sg) * 33 + sc;
; #pragma unroll
;                 for (int e = 0; e < 16; ++e) { av[e] = dir ? ap_[-e * 33] : ap_[e * 33]; uv[e] = dir ? up_[-e * 33] : up_[e * 33]; H = av[e] * H + uv[e]; A *= av[e]; }
;                 segA[sg * 32 + sc] = A; segH[sg * 32 + sc] = H;
;             }
;             const int rbase = dir == 0 ? base + t0 + 32 * wave : base + t0 + LCH - 1 - 32 * wave - 16;
;             float hfv[16]; unsigned grv[16];
;             if (!isctx && dir == 1) {
.LBB0_2180:
	ds_read_b128 v[86:89], v53
	ds_read_b128 v[90:93], v53 offset:64
	v_add_u32_e32 v224, s54, v167
	ds_read_b32 v98, v224
	ds_read_b32 v99, v224 offset:132
	ds_read_b32 v100, v224 offset:264
	ds_read_b32 v101, v224 offset:396
	v_add_u32_e32 v53, 0x900, v53
	s_waitcnt lgkmcnt(5)
	v_mfma_f32_16x16x32_bf16 v[94:97], v[86:89], v[2:5], 0
	s_waitcnt lgkmcnt(4)
	v_mfma_f32_16x16x32_bf16 v[94:97], v[90:93], v[6:9], v[94:97]
	v_mfma_f32_16x16x32_bf16 v[86:89], v[86:89], v[10:13], 0
	v_mfma_f32_16x16x32_bf16 v[86:89], v[90:93], v[14:17], v[86:89]
	s_nop 5
	v_add_f32_e32 v90, v55, v94
	v_mul_f32_e32 v90, 0xbfb8aa3b, v90
	v_exp_f32_e32 v90, v90
	v_add_u32_e32 v92, s54, v167
	v_add_u32_e32 v93, 0x11400, v92
	v_add_f32_e32 v86, v57, v86
	v_add_f32_e32 v90, 1.0, v90
	v_rcp_f32_e32 v90, v90
	v_mul_f32_e32 v86, 0xbfb8aa3b, v86
	v_exp_f32_e32 v86, v86
	v_add_f32_e32 v87, v57, v87
	v_mul_f32_e32 v90, v215, v90
	v_exp_f32_e32 v90, v90
	v_add_f32_e32 v86, 1.0, v86
	v_rcp_f32_e32 v86, v86
	v_mul_f32_e32 v87, 0xbfb8aa3b, v87
	v_fma_f32 v91, -v90, v90, 1.0
	ds_write_b32 v93, v90
	v_sqrt_f32_e32 v90, v91
	v_exp_f32_e32 v87, v87
	v_mul_f32_e32 v86, v86, v90
	v_add_f32_e32 v87, 1.0, v87
	v_rcp_f32_e32 v87, v87
	s_waitcnt lgkmcnt(1)
	v_mul_f32_e32 v86, v98, v86
	v_add_u32_e32 v90, s54, v168
	v_add_u32_e32 v91, 0x19800, v90
	ds_write_b32 v91, v86
	v_add_f32_e32 v86, v55, v95
	v_mul_f32_e32 v86, 0xbfb8aa3b, v86
	v_exp_f32_e32 v86, v86
	v_add_u32_e32 v93, 0x11484, v90
	s_addk_i32 s54, 0x840
	s_cmpk_eq_i32 s54, 0x2100
	v_add_f32_e32 v86, 1.0, v86
	v_rcp_f32_e32 v86, v86
	s_nop 0
	v_mul_f32_e32 v86, v215, v86
	v_exp_f32_e32 v86, v86
	ds_write_b32 v93, v86
	v_fma_f32 v91, -v86, v86, 1.0
	v_sqrt_f32_e32 v86, v91
	v_add_u32_e32 v91, 0x11508, v90
	v_mul_f32_e32 v86, v87, v86
	v_mul_f32_e32 v86, v99, v86
	v_add_u32_e32 v87, 0x19884, v90
	ds_write_b32 v87, v86
	v_add_f32_e32 v86, v55, v96
	v_mul_f32_e32 v86, 0xbfb8aa3b, v86
	v_exp_f32_e32 v86, v86
	v_add_f32_e32 v87, v57, v88
	v_mul_f32_e32 v87, 0xbfb8aa3b, v87
	v_exp_f32_e32 v87, v87
	v_add_f32_e32 v86, 1.0, v86
	v_rcp_f32_e32 v86, v86
	v_add_f32_e32 v87, 1.0, v87
	v_rcp_f32_e32 v87, v87
	v_mul_f32_e32 v86, v215, v86
	v_exp_f32_e32 v86, v86
	ds_write_b32 v91, v86
	v_fma_f32 v88, -v86, v86, 1.0
	v_sqrt_f32_e32 v86, v88
	s_nop 0
	v_mul_f32_e32 v86, v87, v86
	v_mul_f32_e32 v86, v100, v86
	v_add_u32_e32 v87, 0x19908, v90
	ds_write_b32 v87, v86
	v_add_f32_e32 v86, v55, v97
	v_mul_f32_e32 v86, 0xbfb8aa3b, v86
	v_exp_f32_e32 v86, v86
	v_add_f32_e32 v87, v57, v89
	v_mul_f32_e32 v87, 0xbfb8aa3b, v87
	v_exp_f32_e32 v87, v87
	v_add_f32_e32 v86, 1.0, v86
	v_rcp_f32_e32 v86, v86
	v_add_u32_e32 v89, 0x1158c, v90
	v_add_f32_e32 v87, 1.0, v87
	v_rcp_f32_e32 v87, v87
	v_mul_f32_e32 v86, v215, v86
	v_exp_f32_e32 v86, v86
	ds_write_b32 v89, v86
	v_fma_f32 v88, -v86, v86, 1.0
	v_sqrt_f32_e32 v86, v88
	s_nop 0
	v_mul_f32_e32 v86, v87, v86
	v_mul_f32_e32 v86, v86, v101
	v_add_u32_e32 v87, 0x1998c, v92
	ds_write_b32 v87, v86
	s_cbranch_scc0 .LBB0_2180
	v_sub_u32_e64 v53, s69, 1 clamp
	s_waitcnt lgkmcnt(0)
	s_barrier
	v_readfirstlane_b32 s92, v53
	v_add_u32_e32 v53, s70, v216
	v_add_u32_e32 v86, s70, v217
	v_add_u32_e32 v87, s71, v216
	v_add_u32_e32 v88, s71, v217
	v_add_u32_e32 v89, s72, v216
	v_add_u32_e32 v90, s72, v217
	ds_read_b32 v238, v216
	ds_read_b32 v224, v217
	ds_read_b32 v236, v53
	ds_read_b32 v106, v86
	ds_read_b32 v237, v87
	ds_read_b32 v98, v88
	ds_read_b32 v99, v89
	ds_read_b32 v91, v90
	s_waitcnt lgkmcnt(6)
	v_fma_f32 v53, 0, v238, v224
	s_waitcnt lgkmcnt(4)
	v_fma_f32 v53, v53, v236, v106
	v_mul_f32_e32 v86, v238, v236
	s_waitcnt lgkmcnt(2)
	v_fma_f32 v53, v53, v237, v98
	v_mul_f32_e32 v86, v86, v237
	s_waitcnt lgkmcnt(0)
	v_fma_f32 v87, v53, v99, v91
	v_add_u32_e32 v53, s73, v216
	v_add_u32_e32 v93, s75, v217
	v_mul_f32_e32 v86, v86, v99
	v_add_u32_e32 v88, s73, v217
	v_add_u32_e32 v89, s74, v216
	v_add_u32_e32 v90, s74, v217
	v_add_u32_e32 v92, s75, v216
	v_add_u32_e32 v94, s78, v216
	v_add_u32_e32 v96, s78, v217
	ds_read_b32 v232, v53
	ds_read_b32 v225, v88
	ds_read_b32 v227, v89
	ds_read_b32 v101, v90
	ds_read_b32 v103, v92
	ds_read_b32 v93, v93
	ds_read_b32 v95, v94
	ds_read_b32 v53, v96
	s_waitcnt lgkmcnt(7)
	v_mul_f32_e32 v86, v86, v232
	s_waitcnt lgkmcnt(6)
	v_fma_f32 v87, v87, v232, v225
	s_waitcnt lgkmcnt(5)
	v_mul_f32_e32 v86, v86, v227
	s_cmp_lg_u32 s69, 0
	s_waitcnt lgkmcnt(4)
	v_fma_f32 v87, v87, v227, v101
	s_waitcnt lgkmcnt(3)
	v_mul_f32_e32 v86, v86, v103
	v_add_u32_e32 v88, s79, v216
	v_add_u32_e32 v90, s80, v216
	v_add_u32_e32 v94, s81, v216
	v_add_u32_e32 v96, s81, v217
	s_cselect_b64 s[54:55], -1, 0
	s_waitcnt lgkmcnt(2)
	v_fma_f32 v87, v87, v103, v93
	s_waitcnt lgkmcnt(1)
	v_mul_f32_e32 v86, v86, v95
	v_add_u32_e32 v89, s79, v217
	v_add_u32_e32 v92, s80, v217
	v_add_u32_e32 v97, s82, v216
	v_add_u32_e32 v100, s82, v217
	ds_read_b32 v233, v88
	ds_read_b32 v226, v89
	ds_read_b32 v229, v90
	ds_read_b32 v102, v92
	ds_read_b32 v104, v94
	ds_read_b32 v94, v96
	ds_read_b32 v96, v97
	ds_read_b32 v90, v100
	s_and_b64 s[56:57], s[54:55], exec
	s_waitcnt lgkmcnt(8)
	v_fma_f32 v87, v87, v95, v53
	s_waitcnt lgkmcnt(7)
	v_mul_f32_e32 v86, v86, v233
	s_cselect_b32 s56, 7, 0
	s_waitcnt lgkmcnt(6)
	v_fma_f32 v87, v87, v233, v226
	s_waitcnt lgkmcnt(5)
	v_mul_f32_e32 v86, v86, v229
	s_cselect_b32 s91, s68, s67
	s_sub_i32 s93, s56, s92
	s_waitcnt lgkmcnt(4)
	v_fma_f32 v87, v87, v229, v102
	s_waitcnt lgkmcnt(3)
	v_mul_f32_e32 v86, v86, v104
	v_add_u32_e32 v88, s83, v216
	v_add_u32_e32 v92, s88, v216
	v_add_u32_e32 v97, s88, v217
	v_add_u32_e32 v100, s89, v216
	s_and_b64 s[56:57], s[48:49], exec
	s_waitcnt lgkmcnt(2)
	v_fma_f32 v87, v87, v104, v94
	s_waitcnt lgkmcnt(1)
	v_mul_f32_e32 v86, v86, v96
	v_add_u32_e32 v89, s83, v217
	v_add_u32_e32 v235, s89, v217
	v_add_u32_e32 v239, s90, v216
	v_add_u32_e32 v240, s90, v217
	ds_read_b32 v234, v88
	ds_read_b32 v230, v89
	ds_read_b32 v231, v92
	ds_read_b32 v105, v97
	ds_read_b32 v107, v100
	ds_read_b32 v97, v235
	ds_read_b32 v100, v239
	ds_read_b32 v92, v240
	s_cselect_b32 s56, s92, s93
	s_waitcnt lgkmcnt(8)
	v_fma_f32 v87, v87, v96, v90
	s_waitcnt lgkmcnt(7)
	v_mul_f32_e32 v86, v86, v234
	s_lshl_b32 s92, s56, 8
	s_waitcnt lgkmcnt(6)
	v_fma_f32 v87, v87, v234, v230
	s_waitcnt lgkmcnt(5)
	v_mul_f32_e32 v86, v86, v231
	s_sub_i32 s56, s91, s58
	s_waitcnt lgkmcnt(4)
	v_fma_f32 v87, v87, v231, v105
	s_waitcnt lgkmcnt(3)
	v_mul_f32_e32 v86, v86, v107
	s_add_i32 s56, s56, s92
	s_and_b64 s[94:95], s[46:47], s[54:55]
	s_waitcnt lgkmcnt(2)
	v_fma_f32 v87, v87, v107, v97
	s_waitcnt lgkmcnt(1)
	v_mul_f32_e32 v86, v86, v100
	s_addk_i32 s56, 0xef
	s_and_b64 vcc, exec, s[94:95]
	s_waitcnt lgkmcnt(0)
	v_fma_f32 v87, v87, v100, v92
	ds_write_b32 v122, v86
	ds_write_b32 v123, v87
	s_cbranch_vccz .LBB0_2183
; __device__ __forceinline__ void lru_item(const Params& p, LAS unsigned char* lds, int item, int tid, int lane, int wave) {
;     ...
;             if (!isctx && dir == 1) {
;                 const float* hp_ = HF + (size_t)rbase * 1024; const bf16* gp_ = ZO + (size_t)rbase * ZO_LD;
; #pragma unroll
;                 for (int e = 0; e < 16; ++e) { hfv[e] = (hp_ - (size_t)e * 1024)[hoff]; grv[e] = (unsigned)(gp_ - (size_t)e * ZO_LD)[goff]; }
;             }
	s_ashr_i32 s57, s56, 31
	s_lshl_b64 s[94:95], s[56:57], 12
	v_lshl_add_u64 v[88:89], v[80:81], 0, s[94:95]
	v_mad_i64_i32 v[86:87], s[94:95], s56, v180, v[82:83]
	v_add_co_u32_e32 v184, vcc, 0x2000, v86
	global_load_dword v183, v[88:89], off nt
	s_nop 0
	v_addc_co_u32_e32 v185, vcc, 0, v87, vcc
	v_add_co_u32_e32 v188, vcc, 0xffffe000, v88
	global_load_ushort v186, v[184:185], off nt
	s_nop 0
	global_load_dword v184, v[88:89], off offset:-4096 nt
	global_load_ushort v187, v[86:87], off offset:-2048 nt
	v_addc_co_u32_e32 v189, vcc, -1, v89, vcc
	global_load_dword v185, v[188:189], off nt
	v_add_co_u32_e32 v188, vcc, 0xffffd000, v86
	s_movk_i32 s57, 0x8000
	s_nop 0
	v_addc_co_u32_e32 v189, vcc, -1, v87, vcc
	v_add_co_u32_e32 v190, vcc, 0xffffd000, v88
	global_load_ushort v189, v[188:189], off nt
	s_nop 0
	v_addc_co_u32_e32 v191, vcc, -1, v89, vcc
	global_load_dword v188, v[190:191], off nt
	v_add_co_u32_e32 v190, vcc, 0xffffb000, v86
	s_nop 1
	v_addc_co_u32_e32 v191, vcc, -1, v87, vcc
	v_add_co_u32_e32 v192, vcc, 0xffffc000, v88
	global_load_ushort v191, v[190:191], off offset:-2048 nt
	s_nop 0
	v_addc_co_u32_e32 v193, vcc, -1, v89, vcc
	global_load_dword v190, v[192:193], off nt
	v_add_co_u32_e32 v192, vcc, 0xffff8000, v86
	s_nop 1
	v_addc_co_u32_e32 v193, vcc, -1, v87, vcc
	v_add_co_u32_e32 v194, vcc, 0xffffb000, v88
	global_load_ushort v193, v[192:193], off nt
	s_nop 0
	v_addc_co_u32_e32 v195, vcc, -1, v89, vcc
	global_load_dword v192, v[194:195], off nt
	v_add_co_u32_e32 v194, vcc, 0xffff6000, v86
	s_nop 1
	v_addc_co_u32_e32 v195, vcc, -1, v87, vcc
	v_add_co_u32_e32 v196, vcc, 0xffffa000, v88
	global_load_ushort v195, v[194:195], off offset:-2048 nt
	s_nop 0
	v_addc_co_u32_e32 v197, vcc, -1, v89, vcc
	global_load_dword v194, v[196:197], off nt
	v_add_co_u32_e32 v196, vcc, 0xffff3000, v86
	s_nop 1
	v_addc_co_u32_e32 v197, vcc, -1, v87, vcc
	v_add_co_u32_e32 v198, vcc, 0xffff9000, v88
	global_load_ushort v197, v[196:197], off nt
	s_nop 0
	v_addc_co_u32_e32 v199, vcc, -1, v89, vcc
	global_load_dword v196, v[198:199], off nt
	v_add_co_u32_e32 v198, vcc, 0xffff1000, v86
	s_nop 1
	v_addc_co_u32_e32 v199, vcc, -1, v87, vcc
	v_add_co_u32_e32 v200, vcc, s57, v88
	global_load_ushort v199, v[198:199], off offset:-2048 nt
	s_nop 0
	v_addc_co_u32_e32 v201, vcc, -1, v89, vcc
	global_load_dword v198, v[200:201], off nt
	v_add_co_u32_e32 v200, vcc, 0xfffee000, v86
	s_mov_b32 s57, 0xffff6000
	s_nop 0
	v_addc_co_u32_e32 v201, vcc, -1, v87, vcc
	v_add_co_u32_e32 v202, vcc, 0xffff7000, v88
	global_load_ushort v201, v[200:201], off nt
	s_nop 0
	v_addc_co_u32_e32 v203, vcc, -1, v89, vcc
	global_load_dword v200, v[202:203], off nt
	v_add_co_u32_e32 v202, vcc, 0xfffec000, v86
	s_nop 1
	v_addc_co_u32_e32 v203, vcc, -1, v87, vcc
	v_add_co_u32_e32 v204, vcc, s57, v88
	global_load_ushort v203, v[202:203], off offset:-2048 nt
	s_nop 0
	v_addc_co_u32_e32 v205, vcc, -1, v89, vcc
	global_load_dword v202, v[204:205], off nt
	v_add_co_u32_e32 v204, vcc, 0xfffe9000, v86
	s_mov_b32 s57, 0xffff3000
	s_nop 0
	v_addc_co_u32_e32 v205, vcc, -1, v87, vcc
	v_add_co_u32_e32 v206, vcc, 0xffff5000, v88
	global_load_ushort v205, v[204:205], off nt
	s_nop 0
	v_addc_co_u32_e32 v207, vcc, -1, v89, vcc
	global_load_dword v204, v[206:207], off nt
	v_add_co_u32_e32 v206, vcc, 0xfffe7000, v86
	s_nop 1
	v_addc_co_u32_e32 v207, vcc, -1, v87, vcc
	v_add_co_u32_e32 v208, vcc, 0xffff4000, v88
	global_load_ushort v207, v[206:207], off offset:-2048 nt
	s_nop 0
	v_addc_co_u32_e32 v209, vcc, -1, v89, vcc
	global_load_dword v206, v[208:209], off nt
	v_add_co_u32_e32 v208, vcc, 0xfffe4000, v86
	s_nop 1
	v_addc_co_u32_e32 v209, vcc, -1, v87, vcc
	v_add_co_u32_e32 v210, vcc, s57, v88
	global_load_ushort v209, v[208:209], off nt
	s_nop 0
	v_addc_co_u32_e32 v211, vcc, -1, v89, vcc
	global_load_dword v208, v[210:211], off nt
	v_add_co_u32_e32 v210, vcc, 0xfffe2000, v86
	s_nop 1
	v_addc_co_u32_e32 v211, vcc, -1, v87, vcc
	s_waitcnt vmcnt(28)
	v_add_co_u32_e32 v212, vcc, 0xffff2000, v88
	global_load_ushort v211, v[210:211], off offset:-2048 nt
	s_nop 0
	v_addc_co_u32_e32 v213, vcc, -1, v89, vcc
	global_load_dword v210, v[212:213], off nt
	v_add_co_u32_e32 v212, vcc, 0xfffdf000, v86
	s_nop 1
	v_addc_co_u32_e32 v213, vcc, -1, v87, vcc
	v_add_co_u32_e32 v88, vcc, 0xffff1000, v88
	global_load_ushort v213, v[212:213], off nt
	s_nop 0
	v_addc_co_u32_e32 v89, vcc, -1, v89, vcc
	v_add_co_u32_e32 v86, vcc, 0xfffdd000, v86
	global_load_dword v212, v[88:89], off nt
	s_nop 0
	v_addc_co_u32_e32 v87, vcc, -1, v87, vcc
	global_load_ushort v214, v[86:87], off offset:-2048 nt

; #define GAS __attribute__((address_space(1)))
;     __device__ __forceinline__ void operator()(const f32x4 (&acc)[2][2][4][2], const pg8::Unit& u, int wr, int wc, int fr, int fq) const {
;     ...
;         const int row0 = u.pm * 256 + wr * 64 + fr, col0 = u.pn * 256 + wc * 32 + 8 * fq;
;         const int r = u.pm < 64 ? (u.pm >> 3) : 8;
;         const float* gv = gate + (size_t)r * DMODW + col0;
;         f32x4 gvv[2][2];
; #pragma unroll
;         for (int bj = 0; bj < 2; ++bj)
; #pragma unroll
;             for (int n = 0; n < 2; ++n) gvv[bj][n] = *(const f32x4*)(gv + bj * 128 + 4 * n) * coef;
;         if (u.kind >= 2) {
;             GAS float* op = part + (size_t)(u.kind - 2) * (PART_STRIDE / 4) + (size_t)(row0 - M_LAT) * D + col0;
; #pragma unroll
;             for (int ai = 0; ai < 2; ++ai)
; #pragma unroll
;                 for (int m = 0; m < 4; ++m) { const size_t ro = (size_t)(ai * 128 + m * 16) * D;
; #pragma unroll
;                     for (int bj = 0; bj < 2; ++bj)
; #pragma unroll
;                         for (int n = 0; n < 2; ++n) *(GAS f32x4*)(op + ro + bj * 128 + 4 * n) = gvv[bj][n] * acc[ai][bj][m][n]; }
;             return;
;         }
;         const size_t eo = (u.pm < 64 ? (size_t)row0 : (size_t)(row0 - M_LAT)) * D + col0;
;         const void* bsel = u.pm < 64 ? base_lat : base_ctx;
;         const size_t oo = (size_t)row0 * D + col0;
;         if constexpr (!BASE_F32) {
;             u32x4 hb[2][4][2];
; #pragma unroll
;             for (int ai = 0; ai < 2; ++ai)
; #pragma unroll
;                 for (int m = 0; m < 4; ++m)
; #pragma unroll
;                     for (int bj = 0; bj < 2; ++bj) hb[ai][m][bj] = *(const u32x4*)((const _Float16*)bsel + eo + (size_t)(ai * 128 + m * 16) * D + bj * 128);
; #pragma unroll
;             for (int ai = 0; ai < 2; ++ai)
; #pragma unroll
;                 for (int m = 0; m < 4; ++m)
; #pragma unroll
;                     for (int bj = 0; bj < 2; ++bj) { const size_t ro = (size_t)(ai * 128 + m * 16) * D + bj * 128; const u32x4 hv = hb[ai][m][bj];
;                         const f32x4 v0 = h4_to_f32x4((u32x2){hv.x, hv.y}) + gvv[bj][0] * acc[ai][bj][m][0], v1 = h4_to_f32x4((u32x2){hv.z, hv.w}) + gvv[bj][1] * acc[ai][bj][m][1];
;                         if constexpr (OUT_F32) { *(f32x4*)((float*)out + oo + ro) = v0; *(f32x4*)((float*)out + oo + ro + 4) = v1; }
.LBB0_2302:
	v_lshl_add_u32 v146, s18, 8, v200
	v_add_u32_e32 v132, 0xffffc000, v146
	v_cndmask_b32_e32 v132, v132, v146, vcc
	v_lshl_or_b32 v130, s49, 8, v202
	s_add_u32 s22, s88, s22
	v_ashrrev_i32_e32 v133, 31, v132
	s_addc_u32 s23, s89, s23
	v_ashrrev_i32_e32 v131, 31, v130
	v_lshlrev_b64 v[132:133], 12, v[132:133]
	v_lshl_add_u64 v[132:133], s[22:23], 0, v[132:133]
	v_lshlrev_b64 v[148:149], 1, v[130:131]
	v_lshl_add_u64 v[150:151], v[132:133], 0, v[148:149]
	global_load_dwordx4 v[206:209], v[150:151], off nt
	global_load_dwordx4 v[210:213], v[150:151], off offset:256 nt
	s_lshl_b64 s[20:21], s[20:21], 2
	s_add_u32 s20, s36, s20
	s_addc_u32 s21, s37, s21
	v_lshl_add_u64 v[130:131], v[130:131], 2, s[20:21]
	global_load_dwordx4 v[142:145], v[130:131], off
	global_load_dwordx4 v[138:141], v[130:131], off offset:16
	global_load_dwordx4 v[134:137], v[130:131], off offset:512
	s_nop 0
	global_load_dwordx4 v[130:133], v[130:131], off offset:528
	v_add_co_u32_e32 v152, vcc, s35, v150
	v_ashrrev_i32_e32 v147, 31, v146
	s_nop 0
	v_addc_co_u32_e32 v153, vcc, 0, v151, vcc
	global_load_dwordx4 v[214:217], v[152:153], off nt
	global_load_dwordx4 v[218:221], v[152:153], off offset:256 nt
	v_readlane_b32 s20, v253, 52
	v_lshlrev_b64 v[146:147], 12, v[146:147]
	v_readlane_b32 s21, v253, 53
	s_waitcnt vmcnt(0)
	v_cvt_f32_f16_e32 v238, v206
	v_lshl_add_u64 v[146:147], s[20:21], 0, v[146:147]
	v_lshl_add_u64 v[198:199], v[146:147], 0, v[148:149]
	v_add_co_u32_e32 v146, vcc, s44, v150
	v_cvt_f32_f16_sdwa v239, v206 dst_sel:DWORD dst_unused:UNUSED_PAD src0_sel:WORD_1
	s_nop 0
	v_addc_co_u32_e32 v147, vcc, 0, v151, vcc
	v_add_co_u32_e32 v148, vcc, s41, v150
	v_cvt_f32_f16_e32 v206, v209
	s_nop 0
	v_addc_co_u32_e32 v149, vcc, 0, v151, vcc
	v_add_co_u32_e32 v154, vcc, s45, v150
	v_cvt_f32_f16_e32 v240, v208
	s_nop 0
	v_addc_co_u32_e32 v155, vcc, 0, v151, vcc
	v_add_co_u32_e32 v152, vcc, s46, v150
	v_cvt_f32_f16_sdwa v241, v208 dst_sel:DWORD dst_unused:UNUSED_PAD src0_sel:WORD_1
	s_nop 0
	v_addc_co_u32_e32 v153, vcc, 0, v151, vcc
	v_add_co_u32_e32 v156, vcc, s47, v150
	v_cvt_f32_f16_e32 v208, v211
	s_nop 0
	v_addc_co_u32_e32 v157, vcc, 0, v151, vcc
	v_add_co_u32_e32 v226, vcc, s48, v150
	v_cvt_f32_f16_e32 v242, v210
	s_nop 0
	v_addc_co_u32_e32 v227, vcc, 0, v151, vcc
	global_load_dwordx4 v[222:225], v[146:147], off nt
	global_load_dwordx4 v[230:233], v[146:147], off offset:256 nt
	global_load_dwordx4 v[234:237], v[148:149], off nt
	global_load_dwordx4 v[178:181], v[148:149], off offset:256 nt
	global_load_dwordx4 v[174:177], v[154:155], off nt
	global_load_dwordx4 v[170:173], v[154:155], off offset:256 nt
	global_load_dwordx4 v[166:169], v[152:153], off nt
	global_load_dwordx4 v[162:165], v[152:153], off offset:256 nt
	global_load_dwordx4 v[158:161], v[156:157], off nt
	s_nop 0
	global_load_dwordx4 v[154:157], v[156:157], off offset:256 nt
	s_nop 0
	global_load_dwordx4 v[150:153], v[226:227], off nt
	global_load_dwordx4 v[146:149], v[226:227], off offset:256 nt
	v_cvt_f32_f16_e32 v226, v207
	v_cvt_f32_f16_sdwa v227, v207 dst_sel:DWORD dst_unused:UNUSED_PAD src0_sel:WORD_1
	v_cvt_f32_f16_sdwa v207, v209 dst_sel:DWORD dst_unused:UNUSED_PAD src0_sel:WORD_1
	v_cvt_f32_f16_sdwa v209, v211 dst_sel:DWORD dst_unused:UNUSED_PAD src0_sel:WORD_1
	v_cvt_f32_f16_sdwa v243, v210 dst_sel:DWORD dst_unused:UNUSED_PAD src0_sel:WORD_1
	v_cvt_f32_f16_e32 v210, v213
	v_cvt_f32_f16_sdwa v211, v213 dst_sel:DWORD dst_unused:UNUSED_PAD src0_sel:WORD_1
	v_cvt_f32_f16_e32 v244, v212
	v_cvt_f32_f16_sdwa v245, v212 dst_sel:DWORD dst_unused:UNUSED_PAD src0_sel:WORD_1
	v_pk_fma_f32 v[126:127], v[126:127], v[142:143], v[238:239]
	v_pk_fma_f32 v[128:129], v[128:129], v[144:145], v[226:227]
	v_pk_fma_f32 v[212:213], v[122:123], v[138:139], v[240:241]
	v_pk_fma_f32 v[124:125], v[124:125], v[140:141], v[206:207]
	v_cvt_pk_f16_f32 v123, v128, v129
	v_cvt_pk_f16_f32 v122, v126, v127
	v_cvt_pk_f16_f32 v125, v124, v125
	v_cvt_pk_f16_f32 v124, v212, v213
	v_pk_fma_f32 v[118:119], v[118:119], v[134:135], v[242:243]
	global_store_dwordx4 v[198:199], v[122:125], off
	v_pk_fma_f32 v[120:121], v[120:121], v[136:137], v[208:209]
	v_pk_fma_f32 v[112:113], v[112:113], v[132:133], v[210:211]
	v_pk_fma_f32 v[122:123], v[110:111], v[130:131], v[244:245]
	v_cvt_pk_f16_f32 v111, v120, v121
	v_cvt_pk_f16_f32 v110, v118, v119
	v_cvt_pk_f16_f32 v113, v112, v113
	v_cvt_pk_f16_f32 v112, v122, v123
	global_store_dwordx4 v[198:199], v[110:113], off offset:256
	v_cvt_f32_f16_e32 v118, v217
	v_cvt_f32_f16_e32 v120, v216
	v_cvt_f32_f16_e32 v110, v215
	v_cvt_f32_f16_sdwa v111, v215 dst_sel:DWORD dst_unused:UNUSED_PAD src0_sel:WORD_1
	v_cvt_f32_f16_e32 v112, v214
	v_cvt_f32_f16_sdwa v113, v214 dst_sel:DWORD dst_unused:UNUSED_PAD src0_sel:WORD_1
	v_cvt_f32_f16_sdwa v121, v216 dst_sel:DWORD dst_unused:UNUSED_PAD src0_sel:WORD_1
	v_cvt_f32_f16_sdwa v119, v217 dst_sel:DWORD dst_unused:UNUSED_PAD src0_sel:WORD_1
	v_pk_fma_f32 v[110:111], v[116:117], v[144:145], v[110:111]
	v_pk_fma_f32 v[112:113], v[114:115], v[142:143], v[112:113]
	v_pk_fma_f32 v[114:115], v[106:107], v[138:139], v[120:121]
	v_pk_fma_f32 v[108:109], v[108:109], v[140:141], v[118:119]
	v_cvt_pk_f16_f32 v107, v110, v111
	v_add_co_u32_e32 v110, vcc, s35, v198
	v_cvt_pk_f16_f32 v106, v112, v113
	v_cvt_pk_f16_f32 v109, v108, v109
	v_cvt_pk_f16_f32 v108, v114, v115
	v_addc_co_u32_e32 v111, vcc, 0, v199, vcc
	global_store_dwordx4 v[110:111], v[106:109], off
	v_cvt_f32_f16_e32 v112, v221
	v_cvt_f32_f16_e32 v114, v220
	v_cvt_f32_f16_e32 v106, v219
	v_cvt_f32_f16_sdwa v107, v219 dst_sel:DWORD dst_unused:UNUSED_PAD src0_sel:WORD_1
	v_cvt_f32_f16_e32 v108, v218
	v_cvt_f32_f16_sdwa v109, v218 dst_sel:DWORD dst_unused:UNUSED_PAD src0_sel:WORD_1
	v_cvt_f32_f16_sdwa v115, v220 dst_sel:DWORD dst_unused:UNUSED_PAD src0_sel:WORD_1
	v_cvt_f32_f16_sdwa v113, v221 dst_sel:DWORD dst_unused:UNUSED_PAD src0_sel:WORD_1
	v_pk_fma_f32 v[104:105], v[104:105], v[136:137], v[106:107]
	v_pk_fma_f32 v[102:103], v[102:103], v[134:135], v[108:109]
	v_pk_fma_f32 v[106:107], v[94:95], v[130:131], v[114:115]
	v_pk_fma_f32 v[96:97], v[96:97], v[132:133], v[112:113]
	v_cvt_pk_f16_f32 v95, v104, v105
	v_cvt_pk_f16_f32 v94, v102, v103
	v_cvt_pk_f16_f32 v97, v96, v97
	v_cvt_pk_f16_f32 v96, v106, v107
	global_store_dwordx4 v[110:111], v[94:97], off offset:256
	s_waitcnt vmcnt(15)
; __device__ __forceinline__ u32x2 f32x4_to_h4(f32x4 v) { return __builtin_bit_cast(u32x2, __builtin_convertvector(v, f16x4)); }
; __device__ __forceinline__ f32x4 h4_to_f32x4(u32x2 v) { return __builtin_convertvector(__builtin_bit_cast(f16x4, v), f32x4); }
;     __device__ __forceinline__ void operator()(const f32x4 (&acc)[2][2][4][2], const pg8::Unit& u, int wr, int wc, int fr, int fq) const {
;     ...
; #pragma unroll
;             for (int ai = 0; ai < 2; ++ai)
; #pragma unroll
;                 for (int m = 0; m < 4; ++m)
; #pragma unroll
;                     for (int bj = 0; bj < 2; ++bj) { const size_t ro = (size_t)(ai * 128 + m * 16) * D + bj * 128; const u32x4 hv = hb[ai][m][bj];
;                         const f32x4 v0 = h4_to_f32x4((u32x2){hv.x, hv.y}) + gvv[bj][0] * acc[ai][bj][m][0], v1 = h4_to_f32x4((u32x2){hv.z, hv.w}) + gvv[bj][1] * acc[ai][bj][m][1];
;                         if constexpr (OUT_F32) { *(f32x4*)((float*)out + oo + ro) = v0; *(f32x4*)((float*)out + oo + ro + 4) = v1; }
;                         else { const u32x2 h0 = f32x4_to_h4(v0), h1 = f32x4_to_h4(v1); *(u32x4*)((_Float16*)out + oo + ro) = (u32x4){h0.x, h0.y, h1.x, h1.y}; } }
	v_cvt_f32_f16_e32 v102, v225
	v_cvt_f32_f16_e32 v94, v223
	v_cvt_f32_f16_sdwa v95, v223 dst_sel:DWORD dst_unused:UNUSED_PAD src0_sel:WORD_1
	v_cvt_f32_f16_e32 v96, v222
	v_cvt_f32_f16_sdwa v97, v222 dst_sel:DWORD dst_unused:UNUSED_PAD src0_sel:WORD_1
	v_cvt_f32_f16_e32 v104, v224
	v_cvt_f32_f16_sdwa v105, v224 dst_sel:DWORD dst_unused:UNUSED_PAD src0_sel:WORD_1
	v_cvt_f32_f16_sdwa v103, v225 dst_sel:DWORD dst_unused:UNUSED_PAD src0_sel:WORD_1
	v_pk_fma_f32 v[94:95], v[100:101], v[144:145], v[94:95]
	v_pk_fma_f32 v[96:97], v[98:99], v[142:143], v[96:97]
	v_pk_fma_f32 v[98:99], v[90:91], v[138:139], v[104:105]
	v_pk_fma_f32 v[92:93], v[92:93], v[140:141], v[102:103]
	v_cvt_pk_f16_f32 v91, v94, v95
	v_add_co_u32_e32 v94, vcc, s44, v198
	v_cvt_pk_f16_f32 v90, v96, v97
	v_cvt_pk_f16_f32 v93, v92, v93
	v_cvt_pk_f16_f32 v92, v98, v99
	v_addc_co_u32_e32 v95, vcc, 0, v199, vcc
	global_store_dwordx4 v[94:95], v[90:93], off
	s_waitcnt vmcnt(15)
	v_cvt_f32_f16_e32 v96, v233
	v_cvt_f32_f16_e32 v98, v232
	v_cvt_f32_f16_e32 v90, v231
	v_cvt_f32_f16_sdwa v91, v231 dst_sel:DWORD dst_unused:UNUSED_PAD src0_sel:WORD_1
	v_cvt_f32_f16_e32 v92, v230
	v_cvt_f32_f16_sdwa v93, v230 dst_sel:DWORD dst_unused:UNUSED_PAD src0_sel:WORD_1
	v_cvt_f32_f16_sdwa v99, v232 dst_sel:DWORD dst_unused:UNUSED_PAD src0_sel:WORD_1
	v_cvt_f32_f16_sdwa v97, v233 dst_sel:DWORD dst_unused:UNUSED_PAD src0_sel:WORD_1
	v_pk_fma_f32 v[88:89], v[88:89], v[136:137], v[90:91]
	v_pk_fma_f32 v[86:87], v[86:87], v[134:135], v[92:93]
	v_pk_fma_f32 v[90:91], v[78:79], v[130:131], v[98:99]
	v_pk_fma_f32 v[80:81], v[80:81], v[132:133], v[96:97]
	v_cvt_pk_f16_f32 v79, v88, v89
	v_cvt_pk_f16_f32 v78, v86, v87
	v_cvt_pk_f16_f32 v81, v80, v81
	v_cvt_pk_f16_f32 v80, v90, v91
	global_store_dwordx4 v[94:95], v[78:81], off offset:256
	s_waitcnt vmcnt(15)
	v_cvt_f32_f16_e32 v86, v237
	v_cvt_f32_f16_e32 v88, v236
	v_cvt_f32_f16_e32 v78, v235
	v_cvt_f32_f16_sdwa v79, v235 dst_sel:DWORD dst_unused:UNUSED_PAD src0_sel:WORD_1
	v_cvt_f32_f16_e32 v80, v234
	v_cvt_f32_f16_sdwa v81, v234 dst_sel:DWORD dst_unused:UNUSED_PAD src0_sel:WORD_1
	v_cvt_f32_f16_sdwa v89, v236 dst_sel:DWORD dst_unused:UNUSED_PAD src0_sel:WORD_1
	v_cvt_f32_f16_sdwa v87, v237 dst_sel:DWORD dst_unused:UNUSED_PAD src0_sel:WORD_1
	v_pk_fma_f32 v[78:79], v[84:85], v[144:145], v[78:79]
	v_pk_fma_f32 v[80:81], v[82:83], v[142:143], v[80:81]
	v_pk_fma_f32 v[82:83], v[74:75], v[138:139], v[88:89]
	v_pk_fma_f32 v[76:77], v[76:77], v[140:141], v[86:87]
	v_cvt_pk_f16_f32 v75, v78, v79
	v_add_co_u32_e32 v78, vcc, s41, v198
	v_cvt_pk_f16_f32 v74, v80, v81
	v_cvt_pk_f16_f32 v77, v76, v77
	v_cvt_pk_f16_f32 v76, v82, v83
	v_addc_co_u32_e32 v79, vcc, 0, v199, vcc
	global_store_dwordx4 v[78:79], v[74:77], off
	s_waitcnt vmcnt(15)
	v_cvt_f32_f16_e32 v80, v181
	v_cvt_f32_f16_e32 v82, v180
	v_cvt_f32_f16_e32 v74, v179
	v_cvt_f32_f16_sdwa v75, v179 dst_sel:DWORD dst_unused:UNUSED_PAD src0_sel:WORD_1
	v_cvt_f32_f16_e32 v76, v178
	v_cvt_f32_f16_sdwa v77, v178 dst_sel:DWORD dst_unused:UNUSED_PAD src0_sel:WORD_1
	v_cvt_f32_f16_sdwa v83, v180 dst_sel:DWORD dst_unused:UNUSED_PAD src0_sel:WORD_1
	v_cvt_f32_f16_sdwa v81, v181 dst_sel:DWORD dst_unused:UNUSED_PAD src0_sel:WORD_1
	v_pk_fma_f32 v[72:73], v[72:73], v[136:137], v[74:75]
	v_pk_fma_f32 v[70:71], v[70:71], v[134:135], v[76:77]
	v_pk_fma_f32 v[74:75], v[66:67], v[130:131], v[82:83]
	v_pk_fma_f32 v[68:69], v[68:69], v[132:133], v[80:81]
	v_cvt_pk_f16_f32 v67, v72, v73
	v_cvt_pk_f16_f32 v66, v70, v71
	v_cvt_pk_f16_f32 v69, v68, v69
	v_cvt_pk_f16_f32 v68, v74, v75
	global_store_dwordx4 v[78:79], v[66:69], off offset:256
	s_waitcnt vmcnt(15)
	v_cvt_f32_f16_e32 v70, v177
	v_cvt_f32_f16_e32 v72, v176
	v_cvt_f32_f16_e32 v68, v174
	v_cvt_f32_f16_sdwa v69, v174 dst_sel:DWORD dst_unused:UNUSED_PAD src0_sel:WORD_1
	v_cvt_f32_f16_e32 v66, v175
	v_cvt_f32_f16_sdwa v67, v175 dst_sel:DWORD dst_unused:UNUSED_PAD src0_sel:WORD_1
	v_cvt_f32_f16_sdwa v73, v176 dst_sel:DWORD dst_unused:UNUSED_PAD src0_sel:WORD_1
	v_cvt_f32_f16_sdwa v71, v177 dst_sel:DWORD dst_unused:UNUSED_PAD src0_sel:WORD_1
	v_pk_fma_f32 v[62:63], v[62:63], v[142:143], v[68:69]
	v_pk_fma_f32 v[64:65], v[64:65], v[144:145], v[66:67]
	v_pk_fma_f32 v[66:67], v[58:59], v[138:139], v[72:73]
	v_pk_fma_f32 v[60:61], v[60:61], v[140:141], v[70:71]
	v_cvt_pk_f16_f32 v58, v62, v63
	v_add_co_u32_e32 v62, vcc, s45, v198
	v_cvt_pk_f16_f32 v59, v64, v65
	v_cvt_pk_f16_f32 v61, v60, v61
	v_cvt_pk_f16_f32 v60, v66, v67
	v_addc_co_u32_e32 v63, vcc, 0, v199, vcc
	global_store_dwordx4 v[62:63], v[58:61], off
	s_waitcnt vmcnt(15)
	v_cvt_f32_f16_e32 v64, v173
	v_cvt_f32_f16_e32 v66, v172
	v_cvt_f32_f16_e32 v58, v171
	v_cvt_f32_f16_sdwa v59, v171 dst_sel:DWORD dst_unused:UNUSED_PAD src0_sel:WORD_1
	v_cvt_f32_f16_e32 v60, v170
	v_cvt_f32_f16_sdwa v61, v170 dst_sel:DWORD dst_unused:UNUSED_PAD src0_sel:WORD_1
	v_cvt_f32_f16_sdwa v67, v172 dst_sel:DWORD dst_unused:UNUSED_PAD src0_sel:WORD_1
	v_cvt_f32_f16_sdwa v65, v173 dst_sel:DWORD dst_unused:UNUSED_PAD src0_sel:WORD_1
	v_pk_fma_f32 v[56:57], v[56:57], v[136:137], v[58:59]
	v_pk_fma_f32 v[54:55], v[54:55], v[134:135], v[60:61]
	v_pk_fma_f32 v[58:59], v[46:47], v[130:131], v[66:67]
	v_pk_fma_f32 v[48:49], v[48:49], v[132:133], v[64:65]
	v_cvt_pk_f16_f32 v47, v56, v57
	v_cvt_pk_f16_f32 v46, v54, v55
	v_cvt_pk_f16_f32 v49, v48, v49
	v_cvt_pk_f16_f32 v48, v58, v59
	global_store_dwordx4 v[62:63], v[46:49], off offset:256
	s_waitcnt vmcnt(15)
; #define PG8_BAR __builtin_amdgcn_s_barrier()
; __device__ __forceinline__ u32x2 f32x4_to_h4(f32x4 v) { return __builtin_bit_cast(u32x2, __builtin_convertvector(v, f16x4)); }
; __device__ __forceinline__ f32x4 h4_to_f32x4(u32x2 v) { return __builtin_convertvector(__builtin_bit_cast(f16x4, v), f32x4); }
; template <class Epi, class Sched, bool ALIGN_EPI = true, bool SP2 = true>
; __device__ __forceinline__ void gemm_phase(PG8_LAS unsigned char* lds, const int K  , const Sched& S, const Epi& E) {
;     ...
;         if (!has_next) break;
; #pragma unroll
;         for (int a = 0; a < 2; ++a)
; #pragma unroll
;             for (int b = 0; b < 2; ++b)
; #pragma unroll
;                 for (int m = 0; m < 4; ++m)
; #pragma unroll
;                     for (int n = 0; n < 2; ++n) acc[a][b][m][n] = (f32x4){0.f, 0.f, 0.f, 0.f};
;         cur = nxt; cA = nA; cB = nB; ++ui;
;         if constexpr (ALIGN_EPI) { if (wr == 1) PG8_BAR; }
;     __device__ __forceinline__ void operator()(const f32x4 (&acc)[2][2][4][2], const pg8::Unit& u, int wr, int wc, int fr, int fq) const {
;     ...
;             for (int ai = 0; ai < 2; ++ai)
; #pragma unroll
;                 for (int m = 0; m < 4; ++m)
; #pragma unroll
;                     for (int bj = 0; bj < 2; ++bj) { const size_t ro = (size_t)(ai * 128 + m * 16) * D + bj * 128; const u32x4 hv = hb[ai][m][bj];
;                         const f32x4 v0 = h4_to_f32x4((u32x2){hv.x, hv.y}) + gvv[bj][0] * acc[ai][bj][m][0], v1 = h4_to_f32x4((u32x2){hv.z, hv.w}) + gvv[bj][1] * acc[ai][bj][m][1];
;                         if constexpr (OUT_F32) { *(f32x4*)((float*)out + oo + ro) = v0; *(f32x4*)((float*)out + oo + ro + 4) = v1; }
;                         else { const u32x2 h0 = f32x4_to_h4(v0), h1 = f32x4_to_h4(v1); *(u32x4*)((_Float16*)out + oo + ro) = (u32x4){h0.x, h0.y, h1.x, h1.y}; } }
	v_cvt_f32_f16_e32 v54, v169
	v_cvt_f32_f16_e32 v56, v168
	v_cvt_f32_f16_e32 v46, v167
	v_cvt_f32_f16_sdwa v47, v167 dst_sel:DWORD dst_unused:UNUSED_PAD src0_sel:WORD_1
	v_cvt_f32_f16_e32 v48, v166
	v_cvt_f32_f16_sdwa v49, v166 dst_sel:DWORD dst_unused:UNUSED_PAD src0_sel:WORD_1
	v_cvt_f32_f16_sdwa v57, v168 dst_sel:DWORD dst_unused:UNUSED_PAD src0_sel:WORD_1
	v_cvt_f32_f16_sdwa v55, v169 dst_sel:DWORD dst_unused:UNUSED_PAD src0_sel:WORD_1
	v_pk_fma_f32 v[46:47], v[52:53], v[144:145], v[46:47]
	v_pk_fma_f32 v[48:49], v[50:51], v[142:143], v[48:49]
	v_pk_fma_f32 v[50:51], v[42:43], v[138:139], v[56:57]
	v_pk_fma_f32 v[44:45], v[44:45], v[140:141], v[54:55]
	v_cvt_pk_f16_f32 v43, v46, v47
	v_add_co_u32_e32 v46, vcc, s46, v198
	v_cvt_pk_f16_f32 v42, v48, v49
	v_cvt_pk_f16_f32 v45, v44, v45
	v_cvt_pk_f16_f32 v44, v50, v51
	v_addc_co_u32_e32 v47, vcc, 0, v199, vcc
	global_store_dwordx4 v[46:47], v[42:45], off
	s_waitcnt vmcnt(15)
	v_cvt_f32_f16_e32 v48, v165
	v_cvt_f32_f16_e32 v50, v164
	v_cvt_f32_f16_e32 v42, v163
	v_cvt_f32_f16_sdwa v43, v163 dst_sel:DWORD dst_unused:UNUSED_PAD src0_sel:WORD_1
	v_cvt_f32_f16_e32 v44, v162
	v_cvt_f32_f16_sdwa v45, v162 dst_sel:DWORD dst_unused:UNUSED_PAD src0_sel:WORD_1
	v_cvt_f32_f16_sdwa v51, v164 dst_sel:DWORD dst_unused:UNUSED_PAD src0_sel:WORD_1
	v_cvt_f32_f16_sdwa v49, v165 dst_sel:DWORD dst_unused:UNUSED_PAD src0_sel:WORD_1
	v_pk_fma_f32 v[40:41], v[40:41], v[136:137], v[42:43]
	v_pk_fma_f32 v[38:39], v[38:39], v[134:135], v[44:45]
	v_pk_fma_f32 v[42:43], v[30:31], v[130:131], v[50:51]
	v_pk_fma_f32 v[32:33], v[32:33], v[132:133], v[48:49]
	v_cvt_pk_f16_f32 v31, v40, v41
	v_cvt_pk_f16_f32 v30, v38, v39
	v_cvt_pk_f16_f32 v33, v32, v33
	v_cvt_pk_f16_f32 v32, v42, v43
	global_store_dwordx4 v[46:47], v[30:33], off offset:256
	s_waitcnt vmcnt(15)
	v_cvt_f32_f16_e32 v38, v161
	v_cvt_f32_f16_e32 v40, v160
	v_cvt_f32_f16_e32 v30, v159
	v_cvt_f32_f16_sdwa v31, v159 dst_sel:DWORD dst_unused:UNUSED_PAD src0_sel:WORD_1
	v_cvt_f32_f16_e32 v32, v158
	v_cvt_f32_f16_sdwa v33, v158 dst_sel:DWORD dst_unused:UNUSED_PAD src0_sel:WORD_1
	v_cvt_f32_f16_sdwa v41, v160 dst_sel:DWORD dst_unused:UNUSED_PAD src0_sel:WORD_1
	v_cvt_f32_f16_sdwa v39, v161 dst_sel:DWORD dst_unused:UNUSED_PAD src0_sel:WORD_1
	v_pk_fma_f32 v[30:31], v[36:37], v[144:145], v[30:31]
	v_pk_fma_f32 v[32:33], v[34:35], v[142:143], v[32:33]
	v_pk_fma_f32 v[34:35], v[26:27], v[138:139], v[40:41]
	v_pk_fma_f32 v[28:29], v[28:29], v[140:141], v[38:39]
	v_cvt_pk_f16_f32 v27, v30, v31
	v_add_co_u32_e32 v30, vcc, s47, v198
	v_cvt_pk_f16_f32 v26, v32, v33
	v_cvt_pk_f16_f32 v29, v28, v29
	v_cvt_pk_f16_f32 v28, v34, v35
	v_addc_co_u32_e32 v31, vcc, 0, v199, vcc
	global_store_dwordx4 v[30:31], v[26:29], off
	s_waitcnt vmcnt(15)
	v_cvt_f32_f16_e32 v32, v157
	v_cvt_f32_f16_e32 v34, v156
	v_cvt_f32_f16_e32 v26, v155
	v_cvt_f32_f16_sdwa v27, v155 dst_sel:DWORD dst_unused:UNUSED_PAD src0_sel:WORD_1
	v_cvt_f32_f16_e32 v28, v154
	v_cvt_f32_f16_sdwa v29, v154 dst_sel:DWORD dst_unused:UNUSED_PAD src0_sel:WORD_1
	v_cvt_f32_f16_sdwa v35, v156 dst_sel:DWORD dst_unused:UNUSED_PAD src0_sel:WORD_1
	v_cvt_f32_f16_sdwa v33, v157 dst_sel:DWORD dst_unused:UNUSED_PAD src0_sel:WORD_1
	v_pk_fma_f32 v[24:25], v[24:25], v[136:137], v[26:27]
	v_pk_fma_f32 v[22:23], v[22:23], v[134:135], v[28:29]
	v_pk_fma_f32 v[26:27], v[14:15], v[130:131], v[34:35]
	v_pk_fma_f32 v[16:17], v[16:17], v[132:133], v[32:33]
	v_cvt_pk_f16_f32 v15, v24, v25
	v_cvt_pk_f16_f32 v14, v22, v23
	v_cvt_pk_f16_f32 v17, v16, v17
	v_cvt_pk_f16_f32 v16, v26, v27
	global_store_dwordx4 v[30:31], v[14:17], off offset:256
	s_waitcnt vmcnt(15)
	v_cvt_f32_f16_e32 v22, v153
	v_cvt_f32_f16_e32 v24, v152
	v_cvt_f32_f16_e32 v14, v151
	v_cvt_f32_f16_sdwa v15, v151 dst_sel:DWORD dst_unused:UNUSED_PAD src0_sel:WORD_1
	v_cvt_f32_f16_e32 v16, v150
	v_cvt_f32_f16_sdwa v17, v150 dst_sel:DWORD dst_unused:UNUSED_PAD src0_sel:WORD_1
	v_cvt_f32_f16_sdwa v25, v152 dst_sel:DWORD dst_unused:UNUSED_PAD src0_sel:WORD_1
	v_cvt_f32_f16_sdwa v23, v153 dst_sel:DWORD dst_unused:UNUSED_PAD src0_sel:WORD_1
	v_pk_fma_f32 v[14:15], v[20:21], v[144:145], v[14:15]
	v_pk_fma_f32 v[16:17], v[18:19], v[142:143], v[16:17]
	v_pk_fma_f32 v[18:19], v[10:11], v[138:139], v[24:25]
	v_pk_fma_f32 v[12:13], v[12:13], v[140:141], v[22:23]
	v_cvt_pk_f16_f32 v11, v14, v15
	v_add_co_u32_e32 v14, vcc, s48, v198
	v_cvt_pk_f16_f32 v10, v16, v17
	v_cvt_pk_f16_f32 v13, v12, v13
	v_cvt_pk_f16_f32 v12, v18, v19
	v_addc_co_u32_e32 v15, vcc, 0, v199, vcc
	global_store_dwordx4 v[14:15], v[10:13], off
	s_waitcnt vmcnt(15)
	v_cvt_f32_f16_e32 v16, v149
	v_cvt_f32_f16_e32 v18, v148
	v_cvt_f32_f16_e32 v10, v147
	v_cvt_f32_f16_sdwa v11, v147 dst_sel:DWORD dst_unused:UNUSED_PAD src0_sel:WORD_1
	v_cvt_f32_f16_e32 v12, v146
	v_cvt_f32_f16_sdwa v13, v146 dst_sel:DWORD dst_unused:UNUSED_PAD src0_sel:WORD_1
	v_cvt_f32_f16_sdwa v19, v148 dst_sel:DWORD dst_unused:UNUSED_PAD src0_sel:WORD_1
	v_cvt_f32_f16_sdwa v17, v149 dst_sel:DWORD dst_unused:UNUSED_PAD src0_sel:WORD_1
	v_pk_fma_f32 v[8:9], v[8:9], v[136:137], v[10:11]
	v_pk_fma_f32 v[6:7], v[6:7], v[134:135], v[12:13]
	v_pk_fma_f32 v[10:11], v[2:3], v[130:131], v[18:19]
	v_pk_fma_f32 v[4:5], v[4:5], v[132:133], v[16:17]
	v_cvt_pk_f16_f32 v3, v8, v9
	v_cvt_pk_f16_f32 v2, v6, v7
	v_cvt_pk_f16_f32 v5, v4, v5
	v_cvt_pk_f16_f32 v4, v10, v11
	s_andn2_b64 vcc, exec, s[0:1]
	s_mov_b64 s[0:1], -1
	global_store_dwordx4 v[14:15], v[2:5], off offset:256
	s_cbranch_vccnz .LBB0_2288
	s_andn2_b64 vcc, exec, s[4:5]
	s_cbranch_vccnz .LBB0_2287
	s_barrier
	s_branch .LBB0_2287

; __device__ __forceinline__ void lds_barrier() { asm volatile("s_waitcnt lgkmcnt(0)" ::: "memory"); __builtin_amdgcn_s_barrier(); asm volatile("" ::: "memory"); }
; template <bool COMBINE, bool SRC_F32>
; __device__ __forceinline__ void norm_phase(LAS unsigned char* lds, const void* src_lat, const void* src_ctx, _Float16* xw_ctx, const float* part, int nrows, const float* g, const float* modl, int shift_idx, int scale_idx, bf16* HN, int tid, int lane, int wave) {
;     ...
;     if (gw < nrows) NORM_LOAD(v, gw);
;     lds_barrier();
;     for (int row = gw; row < nrows; row += NGW) {
;         if (row + NGW < nrows) NORM_LOAD(nv, row + NGW);
.LBB0_2366:
	s_add_i32 s10, s8, s4
	s_cmpk_gt_i32 s10, 0x3fff
	s_cselect_b64 s[12:13], -1, 0
	s_and_b64 vcc, exec, s[12:13]
	s_cbranch_vccnz .LBB0_2365
	s_ashr_i32 s11, s10, 31
	s_lshl_b64 s[0:1], s[10:11], 12
	v_lshl_add_u64 v[2:3], v[36:37], 0, s[0:1]
	global_load_dwordx4 v[8:11], v[2:3], off nt
	global_load_dwordx4 v[16:19], v[2:3], off offset:1024 nt
	global_load_dwordx4 v[24:27], v[2:3], off offset:2048 nt
	global_load_dwordx4 v[74:77], v[2:3], off offset:3072 nt
	s_waitcnt vmcnt(3)
	v_cvt_f32_f16_e32 v4, v9
	v_cvt_f32_f16_e32 v2, v8
	v_cvt_f32_f16_sdwa v5, v9 dst_sel:DWORD dst_unused:UNUSED_PAD src0_sel:WORD_1
	v_cvt_f32_f16_sdwa v3, v8 dst_sel:DWORD dst_unused:UNUSED_PAD src0_sel:WORD_1
	v_cvt_f32_f16_e32 v8, v11
	v_cvt_f32_f16_e32 v6, v10
	v_cvt_f32_f16_sdwa v9, v11 dst_sel:DWORD dst_unused:UNUSED_PAD src0_sel:WORD_1
	v_cvt_f32_f16_sdwa v7, v10 dst_sel:DWORD dst_unused:UNUSED_PAD src0_sel:WORD_1
	s_waitcnt vmcnt(2)
	v_cvt_f32_f16_e32 v12, v17
	v_cvt_f32_f16_e32 v10, v16
	v_cvt_f32_f16_sdwa v13, v17 dst_sel:DWORD dst_unused:UNUSED_PAD src0_sel:WORD_1
	v_cvt_f32_f16_sdwa v11, v16 dst_sel:DWORD dst_unused:UNUSED_PAD src0_sel:WORD_1
	v_cvt_f32_f16_e32 v16, v19
	v_cvt_f32_f16_e32 v14, v18
	v_cvt_f32_f16_sdwa v17, v19 dst_sel:DWORD dst_unused:UNUSED_PAD src0_sel:WORD_1
	v_cvt_f32_f16_sdwa v15, v18 dst_sel:DWORD dst_unused:UNUSED_PAD src0_sel:WORD_1
	s_waitcnt vmcnt(1)
	v_cvt_f32_f16_e32 v20, v25
	v_cvt_f32_f16_e32 v18, v24
	v_cvt_f32_f16_sdwa v21, v25 dst_sel:DWORD dst_unused:UNUSED_PAD src0_sel:WORD_1
	v_cvt_f32_f16_sdwa v19, v24 dst_sel:DWORD dst_unused:UNUSED_PAD src0_sel:WORD_1
	v_cvt_f32_f16_e32 v24, v27
	v_cvt_f32_f16_e32 v22, v26
	v_cvt_f32_f16_sdwa v25, v27 dst_sel:DWORD dst_unused:UNUSED_PAD src0_sel:WORD_1
	v_cvt_f32_f16_sdwa v23, v26 dst_sel:DWORD dst_unused:UNUSED_PAD src0_sel:WORD_1
	s_waitcnt vmcnt(0)
	v_cvt_f32_f16_e32 v28, v75
	v_cvt_f32_f16_e32 v26, v74
	v_cvt_f32_f16_sdwa v29, v75 dst_sel:DWORD dst_unused:UNUSED_PAD src0_sel:WORD_1
	v_cvt_f32_f16_sdwa v27, v74 dst_sel:DWORD dst_unused:UNUSED_PAD src0_sel:WORD_1
	v_cvt_f32_f16_e32 v32, v77
	v_cvt_f32_f16_e32 v30, v76
	v_cvt_f32_f16_sdwa v33, v77 dst_sel:DWORD dst_unused:UNUSED_PAD src0_sel:WORD_1
	v_cvt_f32_f16_sdwa v31, v76 dst_sel:DWORD dst_unused:UNUSED_PAD src0_sel:WORD_1
	s_branch .LBB0_2365

; #define GAS __attribute__((address_space(1)))
;     __device__ __forceinline__ void operator()(const f32x4 (&acc)[2][2][4][2], const pg8::Unit& u, int wr, int wc, int fr, int fq) const {
;     ...
;         const int row0 = u.pm * 256 + wr * 64 + fr, col0 = u.pn * 256 + wc * 32 + 8 * fq;
;         const int r = u.pm < 64 ? (u.pm >> 3) : 8;
;         const float* gv = gate + (size_t)r * DMODW + col0;
;         f32x4 gvv[2][2];
; #pragma unroll
;         for (int bj = 0; bj < 2; ++bj)
; #pragma unroll
;             for (int n = 0; n < 2; ++n) gvv[bj][n] = *(const f32x4*)(gv + bj * 128 + 4 * n) * coef;
;         if (u.kind >= 2) {
;             GAS float* op = part + (size_t)(u.kind - 2) * (PART_STRIDE / 4) + (size_t)(row0 - M_LAT) * D + col0;
; #pragma unroll
;             for (int ai = 0; ai < 2; ++ai)
; #pragma unroll
;                 for (int m = 0; m < 4; ++m) { const size_t ro = (size_t)(ai * 128 + m * 16) * D;
; #pragma unroll
;                     for (int bj = 0; bj < 2; ++bj)
; #pragma unroll
;                         for (int n = 0; n < 2; ++n) *(GAS f32x4*)(op + ro + bj * 128 + 4 * n) = gvv[bj][n] * acc[ai][bj][m][n]; }
;             return;
;         }
;         const size_t eo = (u.pm < 64 ? (size_t)row0 : (size_t)(row0 - M_LAT)) * D + col0;
;         const void* bsel = u.pm < 64 ? base_lat : base_ctx;
;         const size_t oo = (size_t)row0 * D + col0;
;         if constexpr (!BASE_F32) {
;             u32x4 hb[2][4][2];
; #pragma unroll
;             for (int ai = 0; ai < 2; ++ai)
; #pragma unroll
;                 for (int m = 0; m < 4; ++m)
; #pragma unroll
;                     for (int bj = 0; bj < 2; ++bj) hb[ai][m][bj] = *(const u32x4*)((const _Float16*)bsel + eo + (size_t)(ai * 128 + m * 16) * D + bj * 128);
; #pragma unroll
;             for (int ai = 0; ai < 2; ++ai)
; #pragma unroll
;                 for (int m = 0; m < 4; ++m)
; #pragma unroll
;                     for (int bj = 0; bj < 2; ++bj) { const size_t ro = (size_t)(ai * 128 + m * 16) * D + bj * 128; const u32x4 hv = hb[ai][m][bj];
;                         const f32x4 v0 = h4_to_f32x4((u32x2){hv.x, hv.y}) + gvv[bj][0] * acc[ai][bj][m][0], v1 = h4_to_f32x4((u32x2){hv.z, hv.w}) + gvv[bj][1] * acc[ai][bj][m][1];
;                         if constexpr (OUT_F32) { *(f32x4*)((float*)out + oo + ro) = v0; *(f32x4*)((float*)out + oo + ro + 4) = v1; }
.LBB0_2522:
	s_add_u32 s18, s88, s18
	v_lshl_or_b32 v2, s53, 8, v205
	s_addc_u32 s19, s89, s19
	s_lshl_b64 s[16:17], s[16:17], 2
	v_ashrrev_i32_e32 v3, 31, v2
	s_add_u32 s16, s33, s16
	v_lshl_add_u32 v0, s54, 8, v203
	s_addc_u32 s17, s34, s17
	v_lshlrev_b64 v[4:5], 2, v[2:3]
	v_lshl_add_u64 v[6:7], s[16:17], 0, v[4:5]
	v_add_u32_e32 v1, 0xffffc000, v0
	global_load_dwordx4 v[184:187], v[6:7], off offset:16
	global_load_dwordx4 v[190:193], v[6:7], off
	global_load_dwordx4 v[210:213], v[6:7], off offset:528
	global_load_dwordx4 v[214:217], v[6:7], off offset:512
	v_cndmask_b32_e32 v6, v1, v0, vcc
	v_ashrrev_i32_e32 v7, 31, v6
	v_lshlrev_b64 v[6:7], 12, v[6:7]
	v_lshl_add_u64 v[6:7], s[18:19], 0, v[6:7]
	v_lshl_add_u64 v[2:3], v[2:3], 1, v[6:7]
	global_load_dwordx4 v[218:221], v[2:3], off nt
	global_load_dwordx4 v[222:225], v[2:3], off offset:256 nt
	v_add_co_u32_e32 v6, vcc, s31, v2
	v_ashrrev_i32_e32 v1, 31, v0
	s_nop 0
	v_addc_co_u32_e32 v7, vcc, 0, v3, vcc
	global_load_dwordx4 v[226:229], v[6:7], off nt
	global_load_dwordx4 v[230:233], v[6:7], off offset:256 nt
	v_readlane_b32 s56, v253, 0
	v_lshlrev_b64 v[0:1], 13, v[0:1]
	v_readlane_b32 s62, v253, 6
	v_readlane_b32 s63, v253, 7
	v_readlane_b32 s57, v253, 1
	v_readlane_b32 s58, v253, 2
	v_lshl_add_u64 v[0:1], s[62:63], 0, v[0:1]
	v_lshl_add_u64 v[188:189], v[0:1], 0, v[4:5]
	v_add_co_u32_e32 v0, vcc, s40, v2
	v_readlane_b32 s59, v253, 3
	s_nop 0
	v_addc_co_u32_e32 v1, vcc, 0, v3, vcc
	v_add_co_u32_e32 v4, vcc, s41, v2
	v_readlane_b32 s60, v253, 4
	s_nop 0
	v_addc_co_u32_e32 v5, vcc, 0, v3, vcc
	v_add_co_u32_e32 v6, vcc, s42, v2
	v_readlane_b32 s61, v253, 5
	s_nop 0
	v_addc_co_u32_e32 v7, vcc, 0, v3, vcc
	v_add_co_u32_e32 v8, vcc, s43, v2
	s_waitcnt vmcnt(0)
	v_pk_mul_f32 v[196:197], v[186:187], s[12:13] op_sel_hi:[1,0]
	v_addc_co_u32_e32 v9, vcc, 0, v3, vcc
	v_add_co_u32_e32 v10, vcc, s44, v2
	v_pk_mul_f32 v[198:199], v[192:193], s[12:13] op_sel_hi:[1,0]
	s_nop 0
	v_addc_co_u32_e32 v11, vcc, 0, v3, vcc
	v_add_co_u32_e32 v2, vcc, s45, v2
	v_pk_mul_f32 v[194:195], v[184:185], s[12:13] op_sel_hi:[1,0]
	s_nop 0
	v_addc_co_u32_e32 v3, vcc, 0, v3, vcc
	global_load_dwordx4 v[234:237], v[0:1], off nt
	global_load_dwordx4 v[238:241], v[0:1], off offset:256 nt
	global_load_dwordx4 v[164:167], v[4:5], off nt
	global_load_dwordx4 v[160:163], v[4:5], off offset:256 nt
	global_load_dwordx4 v[28:31], v[6:7], off nt
	global_load_dwordx4 v[24:27], v[6:7], off offset:256 nt
	global_load_dwordx4 v[20:23], v[8:9], off nt
	global_load_dwordx4 v[16:19], v[8:9], off offset:256 nt
	global_load_dwordx4 v[12:15], v[10:11], off nt
	s_nop 0
	global_load_dwordx4 v[8:11], v[10:11], off offset:256 nt
	s_nop 0
	global_load_dwordx4 v[4:7], v[2:3], off nt
	s_nop 0
	global_load_dwordx4 v[0:3], v[2:3], off offset:256 nt
	v_pk_mul_f32 v[192:193], v[214:215], s[12:13] op_sel_hi:[1,0]
	v_pk_mul_f32 v[186:187], v[212:213], s[12:13] op_sel_hi:[1,0]
	v_pk_mul_f32 v[184:185], v[210:211], s[12:13] op_sel_hi:[1,0]
	v_cvt_f32_f16_e32 v210, v218
	v_cvt_f32_f16_sdwa v211, v218 dst_sel:DWORD dst_unused:UNUSED_PAD src0_sel:WORD_1
	v_cvt_f32_f16_e32 v212, v219
	v_cvt_f32_f16_sdwa v213, v219 dst_sel:DWORD dst_unused:UNUSED_PAD src0_sel:WORD_1
	v_cvt_f32_f16_e32 v214, v220
	v_cvt_f32_f16_sdwa v215, v220 dst_sel:DWORD dst_unused:UNUSED_PAD src0_sel:WORD_1
	v_pk_mul_f32 v[200:201], v[190:191], s[12:13] op_sel_hi:[1,0]
	v_pk_mul_f32 v[190:191], v[216:217], s[12:13] op_sel_hi:[1,0]
	v_cvt_f32_f16_e32 v216, v221
	v_cvt_f32_f16_sdwa v217, v221 dst_sel:DWORD dst_unused:UNUSED_PAD src0_sel:WORD_1
	v_pk_fma_f32 v[158:159], v[158:159], v[198:199], v[212:213]
	v_pk_fma_f32 v[156:157], v[156:157], v[200:201], v[210:211]
	v_pk_fma_f32 v[152:153], v[152:153], v[194:195], v[214:215]
	v_cvt_f32_f16_e32 v218, v222
	v_cvt_f32_f16_sdwa v219, v222 dst_sel:DWORD dst_unused:UNUSED_PAD src0_sel:WORD_1
	v_cvt_f32_f16_e32 v220, v223
	v_pk_fma_f32 v[154:155], v[154:155], v[196:197], v[216:217]
	global_store_dwordx4 v[188:189], v[156:159], off nt
	global_store_dwordx4 v[188:189], v[152:155], off offset:16 nt
	v_cvt_f32_f16_sdwa v221, v223 dst_sel:DWORD dst_unused:UNUSED_PAD src0_sel:WORD_1
	v_pk_fma_f32 v[148:149], v[148:149], v[192:193], v[218:219]
	v_cvt_f32_f16_e32 v152, v224
	v_cvt_f32_f16_sdwa v153, v224 dst_sel:DWORD dst_unused:UNUSED_PAD src0_sel:WORD_1
	v_cvt_f32_f16_e32 v154, v225
	v_cvt_f32_f16_sdwa v155, v225 dst_sel:DWORD dst_unused:UNUSED_PAD src0_sel:WORD_1
	v_pk_fma_f32 v[150:151], v[150:151], v[190:191], v[220:221]
	v_pk_fma_f32 v[144:145], v[144:145], v[184:185], v[152:153]
	v_pk_fma_f32 v[146:147], v[146:147], v[186:187], v[154:155]
	global_store_dwordx4 v[188:189], v[148:151], off offset:512 nt
	global_store_dwordx4 v[188:189], v[144:147], off offset:528 nt
	s_nop 0
	v_cvt_f32_f16_e32 v148, v228
	v_cvt_f32_f16_e32 v144, v226
	v_cvt_f32_f16_sdwa v145, v226 dst_sel:DWORD dst_unused:UNUSED_PAD src0_sel:WORD_1
	v_cvt_f32_f16_e32 v146, v227
	v_cvt_f32_f16_sdwa v147, v227 dst_sel:DWORD dst_unused:UNUSED_PAD src0_sel:WORD_1
	v_cvt_f32_f16_e32 v150, v229
	v_cvt_f32_f16_sdwa v151, v229 dst_sel:DWORD dst_unused:UNUSED_PAD src0_sel:WORD_1
	v_cvt_f32_f16_sdwa v149, v228 dst_sel:DWORD dst_unused:UNUSED_PAD src0_sel:WORD_1
	v_pk_fma_f32 v[140:141], v[140:141], v[200:201], v[144:145]
	v_add_co_u32_e32 v144, vcc, s40, v188
	v_pk_fma_f32 v[142:143], v[142:143], v[198:199], v[146:147]
	v_pk_fma_f32 v[138:139], v[138:139], v[196:197], v[150:151]
	v_pk_fma_f32 v[136:137], v[136:137], v[194:195], v[148:149]
	v_addc_co_u32_e32 v145, vcc, 0, v189, vcc
	global_store_dwordx4 v[144:145], v[140:143], off nt
	global_store_dwordx4 v[144:145], v[136:139], off offset:16 nt
	s_nop 0
	v_cvt_f32_f16_e32 v140, v232
	v_cvt_f32_f16_e32 v136, v230
	v_cvt_f32_f16_sdwa v137, v230 dst_sel:DWORD dst_unused:UNUSED_PAD src0_sel:WORD_1
	v_cvt_f32_f16_e32 v138, v231
	v_cvt_f32_f16_sdwa v139, v231 dst_sel:DWORD dst_unused:UNUSED_PAD src0_sel:WORD_1
	v_cvt_f32_f16_sdwa v141, v232 dst_sel:DWORD dst_unused:UNUSED_PAD src0_sel:WORD_1
	v_cvt_f32_f16_e32 v142, v233
	v_cvt_f32_f16_sdwa v143, v233 dst_sel:DWORD dst_unused:UNUSED_PAD src0_sel:WORD_1
	v_pk_fma_f32 v[134:135], v[134:135], v[190:191], v[138:139]
	v_pk_fma_f32 v[132:133], v[132:133], v[192:193], v[136:137]
	v_pk_fma_f32 v[128:129], v[128:129], v[184:185], v[140:141]
	v_pk_fma_f32 v[130:131], v[130:131], v[186:187], v[142:143]
	global_store_dwordx4 v[144:145], v[132:135], off offset:512 nt
	global_store_dwordx4 v[144:145], v[128:131], off offset:528 nt
	s_waitcnt vmcnt(19)
; __device__ __forceinline__ f32x4 h4_to_f32x4(u32x2 v) { return __builtin_convertvector(__builtin_bit_cast(f16x4, v), f32x4); }
;     __device__ __forceinline__ void operator()(const f32x4 (&acc)[2][2][4][2], const pg8::Unit& u, int wr, int wc, int fr, int fq) const {
;     ...
; #pragma unroll
;             for (int ai = 0; ai < 2; ++ai)
; #pragma unroll
;                 for (int m = 0; m < 4; ++m)
; #pragma unroll
;                     for (int bj = 0; bj < 2; ++bj) { const size_t ro = (size_t)(ai * 128 + m * 16) * D + bj * 128; const u32x4 hv = hb[ai][m][bj];
;                         const f32x4 v0 = h4_to_f32x4((u32x2){hv.x, hv.y}) + gvv[bj][0] * acc[ai][bj][m][0], v1 = h4_to_f32x4((u32x2){hv.z, hv.w}) + gvv[bj][1] * acc[ai][bj][m][1];
;                         if constexpr (OUT_F32) { *(f32x4*)((float*)out + oo + ro) = v0; *(f32x4*)((float*)out + oo + ro + 4) = v1; }
	v_cvt_f32_f16_e32 v132, v236
	v_cvt_f32_f16_e32 v128, v234
	v_cvt_f32_f16_sdwa v129, v234 dst_sel:DWORD dst_unused:UNUSED_PAD src0_sel:WORD_1
	v_cvt_f32_f16_e32 v130, v235
	v_cvt_f32_f16_sdwa v131, v235 dst_sel:DWORD dst_unused:UNUSED_PAD src0_sel:WORD_1
	v_cvt_f32_f16_e32 v134, v237
	v_cvt_f32_f16_sdwa v135, v237 dst_sel:DWORD dst_unused:UNUSED_PAD src0_sel:WORD_1
	v_cvt_f32_f16_sdwa v133, v236 dst_sel:DWORD dst_unused:UNUSED_PAD src0_sel:WORD_1
	v_pk_fma_f32 v[124:125], v[124:125], v[200:201], v[128:129]
	v_add_co_u32_e32 v128, vcc, s46, v188
	v_pk_fma_f32 v[126:127], v[126:127], v[198:199], v[130:131]
	v_pk_fma_f32 v[122:123], v[122:123], v[196:197], v[134:135]
	v_pk_fma_f32 v[120:121], v[120:121], v[194:195], v[132:133]
	v_addc_co_u32_e32 v129, vcc, 0, v189, vcc
	global_store_dwordx4 v[128:129], v[124:127], off nt
	global_store_dwordx4 v[128:129], v[120:123], off offset:16 nt
	s_waitcnt vmcnt(20)
	v_cvt_f32_f16_e32 v124, v240
	v_cvt_f32_f16_e32 v120, v238
	v_cvt_f32_f16_sdwa v121, v238 dst_sel:DWORD dst_unused:UNUSED_PAD src0_sel:WORD_1
	v_cvt_f32_f16_e32 v122, v239
	v_cvt_f32_f16_sdwa v123, v239 dst_sel:DWORD dst_unused:UNUSED_PAD src0_sel:WORD_1
	v_cvt_f32_f16_sdwa v125, v240 dst_sel:DWORD dst_unused:UNUSED_PAD src0_sel:WORD_1
	v_cvt_f32_f16_e32 v126, v241
	v_cvt_f32_f16_sdwa v127, v241 dst_sel:DWORD dst_unused:UNUSED_PAD src0_sel:WORD_1
	v_pk_fma_f32 v[118:119], v[118:119], v[190:191], v[122:123]
	v_pk_fma_f32 v[116:117], v[116:117], v[192:193], v[120:121]
	v_pk_fma_f32 v[112:113], v[112:113], v[184:185], v[124:125]
	v_pk_fma_f32 v[114:115], v[114:115], v[186:187], v[126:127]
	global_store_dwordx4 v[128:129], v[116:119], off offset:512 nt
	global_store_dwordx4 v[128:129], v[112:115], off offset:528 nt
	s_waitcnt vmcnt(21)
	v_cvt_f32_f16_e32 v116, v166
	v_cvt_f32_f16_e32 v112, v164
	v_cvt_f32_f16_sdwa v113, v164 dst_sel:DWORD dst_unused:UNUSED_PAD src0_sel:WORD_1
	v_cvt_f32_f16_e32 v114, v165
	v_cvt_f32_f16_sdwa v115, v165 dst_sel:DWORD dst_unused:UNUSED_PAD src0_sel:WORD_1
	v_cvt_f32_f16_e32 v118, v167
	v_cvt_f32_f16_sdwa v119, v167 dst_sel:DWORD dst_unused:UNUSED_PAD src0_sel:WORD_1
	v_cvt_f32_f16_sdwa v117, v166 dst_sel:DWORD dst_unused:UNUSED_PAD src0_sel:WORD_1
	v_pk_fma_f32 v[108:109], v[108:109], v[200:201], v[112:113]
	v_add_co_u32_e32 v112, vcc, s47, v188
	v_pk_fma_f32 v[110:111], v[110:111], v[198:199], v[114:115]
	v_pk_fma_f32 v[106:107], v[106:107], v[196:197], v[118:119]
	v_pk_fma_f32 v[104:105], v[104:105], v[194:195], v[116:117]
	v_addc_co_u32_e32 v113, vcc, 0, v189, vcc
	global_store_dwordx4 v[112:113], v[108:111], off nt
	global_store_dwordx4 v[112:113], v[104:107], off offset:16 nt
	s_waitcnt vmcnt(22)
	v_cvt_f32_f16_e32 v108, v162
	v_cvt_f32_f16_e32 v104, v160
	v_cvt_f32_f16_sdwa v105, v160 dst_sel:DWORD dst_unused:UNUSED_PAD src0_sel:WORD_1
	v_cvt_f32_f16_e32 v106, v161
	v_cvt_f32_f16_sdwa v107, v161 dst_sel:DWORD dst_unused:UNUSED_PAD src0_sel:WORD_1
	v_cvt_f32_f16_sdwa v109, v162 dst_sel:DWORD dst_unused:UNUSED_PAD src0_sel:WORD_1
	v_cvt_f32_f16_e32 v110, v163
	v_cvt_f32_f16_sdwa v111, v163 dst_sel:DWORD dst_unused:UNUSED_PAD src0_sel:WORD_1
	v_pk_fma_f32 v[102:103], v[102:103], v[190:191], v[106:107]
	v_pk_fma_f32 v[100:101], v[100:101], v[192:193], v[104:105]
	v_pk_fma_f32 v[96:97], v[96:97], v[184:185], v[108:109]
	v_pk_fma_f32 v[98:99], v[98:99], v[186:187], v[110:111]
	global_store_dwordx4 v[112:113], v[100:103], off offset:512 nt
	global_store_dwordx4 v[112:113], v[96:99], off offset:528 nt
	s_waitcnt vmcnt(23)
	v_cvt_f32_f16_e32 v100, v31
	v_cvt_f32_f16_e32 v96, v28
	v_cvt_f32_f16_sdwa v97, v28 dst_sel:DWORD dst_unused:UNUSED_PAD src0_sel:WORD_1
	v_cvt_f32_f16_e32 v28, v29
	v_cvt_f32_f16_sdwa v29, v29 dst_sel:DWORD dst_unused:UNUSED_PAD src0_sel:WORD_1
	v_cvt_f32_f16_e32 v98, v30
	v_cvt_f32_f16_sdwa v99, v30 dst_sel:DWORD dst_unused:UNUSED_PAD src0_sel:WORD_1
	v_cvt_f32_f16_sdwa v101, v31 dst_sel:DWORD dst_unused:UNUSED_PAD src0_sel:WORD_1
	v_pk_fma_f32 v[30:31], v[94:95], v[198:199], v[28:29]
	v_pk_fma_f32 v[28:29], v[92:93], v[200:201], v[96:97]
	v_add_co_u32_e32 v92, vcc, s48, v188
	v_pk_fma_f32 v[88:89], v[88:89], v[194:195], v[98:99]
	s_nop 0
	v_addc_co_u32_e32 v93, vcc, 0, v189, vcc
	v_pk_fma_f32 v[90:91], v[90:91], v[196:197], v[100:101]
	global_store_dwordx4 v[92:93], v[28:31], off nt
	global_store_dwordx4 v[92:93], v[88:91], off offset:16 nt
	s_waitcnt vmcnt(24)
	v_cvt_f32_f16_e32 v28, v24
	v_cvt_f32_f16_sdwa v29, v24 dst_sel:DWORD dst_unused:UNUSED_PAD src0_sel:WORD_1
	v_cvt_f32_f16_e32 v24, v25
	v_cvt_f32_f16_sdwa v25, v25 dst_sel:DWORD dst_unused:UNUSED_PAD src0_sel:WORD_1
	v_cvt_f32_f16_e32 v88, v26
	v_cvt_f32_f16_sdwa v89, v26 dst_sel:DWORD dst_unused:UNUSED_PAD src0_sel:WORD_1
	v_cvt_f32_f16_e32 v30, v27
	v_cvt_f32_f16_sdwa v31, v27 dst_sel:DWORD dst_unused:UNUSED_PAD src0_sel:WORD_1
	v_pk_fma_f32 v[26:27], v[86:87], v[190:191], v[24:25]
	v_pk_fma_f32 v[24:25], v[84:85], v[192:193], v[28:29]
	v_pk_fma_f32 v[28:29], v[80:81], v[184:185], v[88:89]
	v_pk_fma_f32 v[30:31], v[82:83], v[186:187], v[30:31]
	global_store_dwordx4 v[92:93], v[24:27], off offset:512 nt
	global_store_dwordx4 v[92:93], v[28:31], off offset:528 nt
	s_waitcnt vmcnt(25)
; #define PG8_BAR __builtin_amdgcn_s_barrier()
; __device__ __forceinline__ f32x4 h4_to_f32x4(u32x2 v) { return __builtin_convertvector(__builtin_bit_cast(f16x4, v), f32x4); }
; template <class Epi, class Sched, bool ALIGN_EPI = true, bool SP2 = true>
; __device__ __forceinline__ void gemm_phase(PG8_LAS unsigned char* lds, const int K  , const Sched& S, const Epi& E) {
;     ...
;         if (!has_next) break;
; #pragma unroll
;         for (int a = 0; a < 2; ++a)
; #pragma unroll
;             for (int b = 0; b < 2; ++b)
; #pragma unroll
;                 for (int m = 0; m < 4; ++m)
; #pragma unroll
;                     for (int n = 0; n < 2; ++n) acc[a][b][m][n] = (f32x4){0.f, 0.f, 0.f, 0.f};
;         cur = nxt; cA = nA; cB = nB; ++ui;
;         if constexpr (ALIGN_EPI) { if (wr == 1) PG8_BAR; }
;     __device__ __forceinline__ void operator()(const f32x4 (&acc)[2][2][4][2], const pg8::Unit& u, int wr, int wc, int fr, int fq) const {
;     ...
; #pragma unroll
;             for (int ai = 0; ai < 2; ++ai)
; #pragma unroll
;                 for (int m = 0; m < 4; ++m)
; #pragma unroll
;                     for (int bj = 0; bj < 2; ++bj) { const size_t ro = (size_t)(ai * 128 + m * 16) * D + bj * 128; const u32x4 hv = hb[ai][m][bj];
;                         const f32x4 v0 = h4_to_f32x4((u32x2){hv.x, hv.y}) + gvv[bj][0] * acc[ai][bj][m][0], v1 = h4_to_f32x4((u32x2){hv.z, hv.w}) + gvv[bj][1] * acc[ai][bj][m][1];
;                         if constexpr (OUT_F32) { *(f32x4*)((float*)out + oo + ro) = v0; *(f32x4*)((float*)out + oo + ro + 4) = v1; }
	v_cvt_f32_f16_e32 v24, v20
	v_cvt_f32_f16_sdwa v25, v20 dst_sel:DWORD dst_unused:UNUSED_PAD src0_sel:WORD_1
	v_cvt_f32_f16_e32 v20, v21
	v_cvt_f32_f16_sdwa v21, v21 dst_sel:DWORD dst_unused:UNUSED_PAD src0_sel:WORD_1
	v_cvt_f32_f16_e32 v28, v22
	v_cvt_f32_f16_sdwa v29, v22 dst_sel:DWORD dst_unused:UNUSED_PAD src0_sel:WORD_1
	v_cvt_f32_f16_e32 v26, v23
	v_cvt_f32_f16_sdwa v27, v23 dst_sel:DWORD dst_unused:UNUSED_PAD src0_sel:WORD_1
	v_pk_fma_f32 v[22:23], v[78:79], v[198:199], v[20:21]
	v_pk_fma_f32 v[20:21], v[76:77], v[200:201], v[24:25]
	v_pk_fma_f32 v[24:25], v[72:73], v[194:195], v[28:29]
	v_add_co_u32_e32 v28, vcc, s49, v188
	v_pk_fma_f32 v[26:27], v[74:75], v[196:197], v[26:27]
	s_nop 0
	v_addc_co_u32_e32 v29, vcc, 0, v189, vcc
	global_store_dwordx4 v[28:29], v[20:23], off nt
	global_store_dwordx4 v[28:29], v[24:27], off offset:16 nt
	s_waitcnt vmcnt(26)
	v_cvt_f32_f16_e32 v20, v16
	v_cvt_f32_f16_sdwa v21, v16 dst_sel:DWORD dst_unused:UNUSED_PAD src0_sel:WORD_1
	v_cvt_f32_f16_e32 v16, v17
	v_cvt_f32_f16_sdwa v17, v17 dst_sel:DWORD dst_unused:UNUSED_PAD src0_sel:WORD_1
	v_cvt_f32_f16_e32 v24, v18
	v_cvt_f32_f16_sdwa v25, v18 dst_sel:DWORD dst_unused:UNUSED_PAD src0_sel:WORD_1
	v_cvt_f32_f16_e32 v22, v19
	v_cvt_f32_f16_sdwa v23, v19 dst_sel:DWORD dst_unused:UNUSED_PAD src0_sel:WORD_1
	v_pk_fma_f32 v[18:19], v[70:71], v[190:191], v[16:17]
	v_pk_fma_f32 v[16:17], v[68:69], v[192:193], v[20:21]
	v_pk_fma_f32 v[20:21], v[64:65], v[184:185], v[24:25]
	v_pk_fma_f32 v[22:23], v[66:67], v[186:187], v[22:23]
	global_store_dwordx4 v[28:29], v[16:19], off offset:512 nt
	global_store_dwordx4 v[28:29], v[20:23], off offset:528 nt
	s_waitcnt vmcnt(27)
	v_cvt_f32_f16_e32 v16, v12
	v_cvt_f32_f16_sdwa v17, v12 dst_sel:DWORD dst_unused:UNUSED_PAD src0_sel:WORD_1
	v_cvt_f32_f16_e32 v12, v13
	v_cvt_f32_f16_sdwa v13, v13 dst_sel:DWORD dst_unused:UNUSED_PAD src0_sel:WORD_1
	v_cvt_f32_f16_e32 v20, v14
	v_cvt_f32_f16_sdwa v21, v14 dst_sel:DWORD dst_unused:UNUSED_PAD src0_sel:WORD_1
	v_cvt_f32_f16_e32 v18, v15
	v_cvt_f32_f16_sdwa v19, v15 dst_sel:DWORD dst_unused:UNUSED_PAD src0_sel:WORD_1
	v_pk_fma_f32 v[14:15], v[62:63], v[198:199], v[12:13]
	v_pk_fma_f32 v[12:13], v[60:61], v[200:201], v[16:17]
	v_pk_fma_f32 v[16:17], v[56:57], v[194:195], v[20:21]
	v_add_co_u32_e32 v20, vcc, s50, v188
	v_pk_fma_f32 v[18:19], v[58:59], v[196:197], v[18:19]
	s_nop 0
	v_addc_co_u32_e32 v21, vcc, 0, v189, vcc
	global_store_dwordx4 v[20:21], v[12:15], off nt
	global_store_dwordx4 v[20:21], v[16:19], off offset:16 nt
	s_waitcnt vmcnt(28)
	v_cvt_f32_f16_e32 v12, v8
	v_cvt_f32_f16_sdwa v13, v8 dst_sel:DWORD dst_unused:UNUSED_PAD src0_sel:WORD_1
	v_cvt_f32_f16_e32 v8, v9
	v_cvt_f32_f16_sdwa v9, v9 dst_sel:DWORD dst_unused:UNUSED_PAD src0_sel:WORD_1
	v_cvt_f32_f16_e32 v16, v10
	v_cvt_f32_f16_sdwa v17, v10 dst_sel:DWORD dst_unused:UNUSED_PAD src0_sel:WORD_1
	v_cvt_f32_f16_e32 v14, v11
	v_cvt_f32_f16_sdwa v15, v11 dst_sel:DWORD dst_unused:UNUSED_PAD src0_sel:WORD_1
	v_pk_fma_f32 v[10:11], v[54:55], v[190:191], v[8:9]
	v_pk_fma_f32 v[8:9], v[52:53], v[192:193], v[12:13]
	v_pk_fma_f32 v[12:13], v[48:49], v[184:185], v[16:17]
	v_pk_fma_f32 v[14:15], v[50:51], v[186:187], v[14:15]
	global_store_dwordx4 v[20:21], v[8:11], off offset:512 nt
	global_store_dwordx4 v[20:21], v[12:15], off offset:528 nt
	s_waitcnt vmcnt(29)
	v_cvt_f32_f16_e32 v8, v4
	v_cvt_f32_f16_sdwa v9, v4 dst_sel:DWORD dst_unused:UNUSED_PAD src0_sel:WORD_1
	v_cvt_f32_f16_e32 v4, v5
	v_cvt_f32_f16_sdwa v5, v5 dst_sel:DWORD dst_unused:UNUSED_PAD src0_sel:WORD_1
	v_cvt_f32_f16_e32 v12, v6
	v_cvt_f32_f16_sdwa v13, v6 dst_sel:DWORD dst_unused:UNUSED_PAD src0_sel:WORD_1
	v_cvt_f32_f16_e32 v10, v7
	v_cvt_f32_f16_sdwa v11, v7 dst_sel:DWORD dst_unused:UNUSED_PAD src0_sel:WORD_1
	v_pk_fma_f32 v[6:7], v[46:47], v[198:199], v[4:5]
	v_pk_fma_f32 v[4:5], v[44:45], v[200:201], v[8:9]
	v_pk_fma_f32 v[8:9], v[40:41], v[194:195], v[12:13]
	v_add_co_u32_e32 v12, vcc, s29, v188
	v_pk_fma_f32 v[10:11], v[42:43], v[196:197], v[10:11]
	s_nop 0
	v_addc_co_u32_e32 v13, vcc, 0, v189, vcc
	global_store_dwordx4 v[12:13], v[4:7], off nt
	global_store_dwordx4 v[12:13], v[8:11], off offset:16 nt
	s_and_b64 vcc, exec, s[0:1]
	s_waitcnt vmcnt(30)
	v_cvt_f32_f16_e32 v4, v0
	v_cvt_f32_f16_sdwa v5, v0 dst_sel:DWORD dst_unused:UNUSED_PAD src0_sel:WORD_1
	v_cvt_f32_f16_e32 v0, v1
	v_cvt_f32_f16_sdwa v1, v1 dst_sel:DWORD dst_unused:UNUSED_PAD src0_sel:WORD_1
	v_cvt_f32_f16_e32 v8, v2
	v_cvt_f32_f16_e32 v6, v3
	v_cvt_f32_f16_sdwa v7, v3 dst_sel:DWORD dst_unused:UNUSED_PAD src0_sel:WORD_1
	v_cvt_f32_f16_sdwa v9, v2 dst_sel:DWORD dst_unused:UNUSED_PAD src0_sel:WORD_1
	v_pk_fma_f32 v[2:3], v[38:39], v[190:191], v[0:1]
	v_pk_fma_f32 v[0:1], v[36:37], v[192:193], v[4:5]
	s_mov_b64 s[0:1], -1
	v_pk_fma_f32 v[6:7], v[34:35], v[186:187], v[6:7]
	v_pk_fma_f32 v[4:5], v[32:33], v[184:185], v[8:9]
	global_store_dwordx4 v[12:13], v[0:3], off offset:512 nt
	global_store_dwordx4 v[12:13], v[4:7], off offset:528 nt
	s_cbranch_vccnz .LBB0_2504
	s_andn2_b64 vcc, exec, s[4:5]
	s_cbranch_vccnz .LBB0_2503
	s_barrier
	s_branch .LBB0_2503
